# v021 + saddr LDS-DMA form for 9 of 16 pieces of the residual-epilogue GEMM loop + 36 duplicate lgkmcnt(0) waits before MFMA blocks removed
# speedup vs baseline: 1.0520x; 1.0052x over previous
; #define PG8_STAGE(bufoff, gbase, voff) do { _Pragma("unroll") for (int _i = 0; _i < 2; ++_i) \
;         __builtin_amdgcn_global_load_lds((const unsigned*)((const char*)(gbase) + (voff)[_i]), (LAS unsigned*)(lds + (bufoff) + ldsw + _i * 8192), 16, 0, 0); } while (0)
; #define PG8_LDA(dst, b, h) do { _Pragma("unroll") for (int m = 0; m < 4; ++m) _Pragma("unroll") for (int k = 0; k < 2; ++k) dst[m][k] = *(const LAS bf16x8*)(lds + PG8_SA(b, h) + aoff + m * 2048 + k * 1024); } while (0)
; #define PG8_LDB(dst, b, h) do { _Pragma("unroll") for (int n = 0; n < 2; ++n) _Pragma("unroll") for (int k = 0; k < 2; ++k) dst[n][k] = *(const LAS bf16x8*)(lds + PG8_SB(b, h) + boff + n * 2048 + k * 1024); } while (0)
; #define PG8_MMA(ai, bj, At, Bt) do { __builtin_amdgcn_s_setprio(1); _Pragma("unroll") for (int m = 0; m < 4; ++m) _Pragma("unroll") for (int n = 0; n < 2; ++n) _Pragma("unroll") for (int k = 0; k < 2; ++k) \
;         acc[ai][bj][m][n] = __builtin_amdgcn_mfma_f32_16x16x32_bf16(Bt[n][k], At[m][k], acc[ai][bj][m][n], 0, 0, 0); __builtin_amdgcn_s_setprio(0); } while (0)
; #define PG8_WAIT_V(n) asm volatile("s_waitcnt vmcnt(" #n ")" ::: "memory")
; #define PG8_WAIT_L(n) asm volatile("s_waitcnt lgkmcnt(" #n ")" ::: "memory")
; template <class Epi>
; __device__ __forceinline__ void gemm_phase(LAS unsigned char* lds, const Gemm g, const StaticOrder& S, const Epi& E) {
;     ...
;         for (int t = 0; t < nt; t += 2) {
;             const bool last = (t == nt - 2);
;             const char* a1 = cA + (size_t)(t + 1) * kstep;
;             const char* a2 = last ? nA : cA + (size_t)(t + 2) * kstep; const char* b2 = last ? nB : cB + (size_t)(t + 2) * kstep;
;             const char* a3 = a2 + kstep; const char* b3 = b2 + kstep;
;             PG8_LDB(B0, 0, 0); PG8_SCHED; PG8_LDA(At, 0, 0); PG8_STAGE(PG8_SA(1, 1), a1 + hstep, voffA);
;             PG8_WAIT_L(8); PG8_BAR; PG8_WAIT_L(0); PG8_MMA(0, 0, At, B0); PG8_BAR; PG8_SCHED;
;             PG8_LDB(B1, 0, 1); PG8_STAGE(PG8_SB(0, 0), b2, voffB);
;             PG8_BAR; PG8_WAIT_L(0); PG8_MMA(0, 1, At, B1); PG8_BAR;
;             PG8_LDA(At, 0, 1); PG8_STAGE(PG8_SA(0, 0), a2, voffA);
;             PG8_BAR; PG8_WAIT_L(0); PG8_MMA(1, 0, At, B0); PG8_BAR; PG8_SCHED;
;             PG8_STAGE(PG8_SB(0, 1), b2 + hstep, voffB);
;             PG8_WAIT_V(6); PG8_BAR; PG8_MMA(1, 1, At, B1); PG8_BAR;
.LBB0_43:
	s_add_u32 s24, s22, 0xfffc0080
	s_addc_u32 s25, s23, -1
	s_add_i32 s47, 0, 0x10000
	ds_read_b128 v[128:131], v247
	ds_read_b128 v[132:135], v247 offset:1024
	ds_read_b128 v[136:139], v247 offset:2048
	ds_read_b128 v[140:143], v247 offset:3072
	s_cmp_eq_u32 s46, 12
	s_cselect_b32 s27, s3, s25
	s_cselect_b32 s26, s9, s24
	s_cselect_b32 s25, s13, s45
	s_cselect_b32 s24, s15, s43
	s_add_i32 m0, s21, 0xc000
	ds_read_b128 v[144:147], v249
	ds_read_b128 v[148:151], v249 offset:1024
	ds_read_b128 v[152:155], v249 offset:2048
	ds_read_b128 v[156:159], v249 offset:3072
	ds_read_b128 v[160:163], v249 offset:4096
	ds_read_b128 v[164:167], v249 offset:5120
	ds_read_b128 v[168:171], v249 offset:6144
	ds_read_b128 v[172:175], v249 offset:7168
	global_load_lds_dwordx4 v214, s[22:23]
	s_add_i32 m0, s21, 0xe000
	s_nop 0
	global_load_lds_dwordx4 v216, s[22:23]
	s_waitcnt lgkmcnt(8)
	s_barrier
	s_waitcnt lgkmcnt(0)
	v_mfma_f32_16x16x32_bf16 v[124:127], v[128:131], v[144:147], v[124:127]
	v_mfma_f32_16x16x32_bf16 v[124:127], v[132:135], v[148:151], v[124:127]
	v_mfma_f32_16x16x32_bf16 v[108:111], v[128:131], v[152:155], v[108:111]
	v_mfma_f32_16x16x32_bf16 v[108:111], v[132:135], v[156:159], v[108:111]
	v_mfma_f32_16x16x32_bf16 v[92:95], v[128:131], v[160:163], v[92:95]
	v_mfma_f32_16x16x32_bf16 v[92:95], v[132:135], v[164:167], v[92:95]
	v_mfma_f32_16x16x32_bf16 v[76:79], v[128:131], v[168:171], v[76:79]
	v_mfma_f32_16x16x32_bf16 v[76:79], v[132:135], v[172:175], v[76:79]
	v_mfma_f32_16x16x32_bf16 v[72:75], v[136:139], v[168:171], v[72:75]
	v_mfma_f32_16x16x32_bf16 v[72:75], v[140:143], v[172:175], v[72:75]
	v_mfma_f32_16x16x32_bf16 v[88:91], v[136:139], v[160:163], v[88:91]
	v_mfma_f32_16x16x32_bf16 v[88:91], v[140:143], v[164:167], v[88:91]
	v_mfma_f32_16x16x32_bf16 v[104:107], v[136:139], v[152:155], v[104:107]
	v_mfma_f32_16x16x32_bf16 v[104:107], v[140:143], v[156:159], v[104:107]
	v_mfma_f32_16x16x32_bf16 v[120:123], v[136:139], v[144:147], v[120:123]
	v_mfma_f32_16x16x32_bf16 v[120:123], v[140:143], v[148:151], v[120:123]
	s_barrier
	s_add_i32 s52, 0, 0x14000
	s_add_i32 s47, s47, s36
	ds_read_b128 v[176:179], v247 offset:16384
	ds_read_b128 v[180:183], v247 offset:17408
	ds_read_b128 v[204:207], v247 offset:18432
	ds_read_b128 v[218:221], v247 offset:19456
	s_mov_b32 m0, s47
	s_add_u32 s98, s24, s58
	s_addc_u32 s99, s25, s59
	global_load_lds_dwordx4 v184, s[24:25]
	s_add_i32 m0, s47, 0x2000
	s_nop 0
	global_load_lds_dwordx4 v212, s[24:25]
	s_barrier
	s_waitcnt lgkmcnt(0)
	v_mfma_f32_16x16x32_bf16 v[116:119], v[176:179], v[144:147], v[116:119]
	v_mfma_f32_16x16x32_bf16 v[116:119], v[180:183], v[148:151], v[116:119]
	v_mfma_f32_16x16x32_bf16 v[100:103], v[176:179], v[152:155], v[100:103]
	v_mfma_f32_16x16x32_bf16 v[100:103], v[180:183], v[156:159], v[100:103]
	v_mfma_f32_16x16x32_bf16 v[84:87], v[176:179], v[160:163], v[84:87]
	v_mfma_f32_16x16x32_bf16 v[84:87], v[180:183], v[164:167], v[84:87]
	v_mfma_f32_16x16x32_bf16 v[68:71], v[176:179], v[168:171], v[68:71]
	v_mfma_f32_16x16x32_bf16 v[68:71], v[180:183], v[172:175], v[68:71]
	v_mfma_f32_16x16x32_bf16 v[64:67], v[204:207], v[168:171], v[64:67]
	v_mfma_f32_16x16x32_bf16 v[64:67], v[218:221], v[172:175], v[64:67]
	v_mfma_f32_16x16x32_bf16 v[80:83], v[204:207], v[160:163], v[80:83]
	v_mfma_f32_16x16x32_bf16 v[80:83], v[218:221], v[164:167], v[80:83]
	v_mfma_f32_16x16x32_bf16 v[96:99], v[204:207], v[152:155], v[96:99]
	v_mfma_f32_16x16x32_bf16 v[96:99], v[218:221], v[156:159], v[96:99]
	v_mfma_f32_16x16x32_bf16 v[112:115], v[204:207], v[144:147], v[112:115]
	v_mfma_f32_16x16x32_bf16 v[112:115], v[218:221], v[148:151], v[112:115]
	s_mov_b32 m0, s21
	s_barrier
	ds_read_b128 v[144:147], v249 offset:16384
	ds_read_b128 v[148:151], v249 offset:17408
	ds_read_b128 v[152:155], v249 offset:18432
	ds_read_b128 v[156:159], v249 offset:19456
	ds_read_b128 v[160:163], v249 offset:20480
	ds_read_b128 v[164:167], v249 offset:21504
	ds_read_b128 v[168:171], v249 offset:22528
	ds_read_b128 v[172:175], v249 offset:23552
	global_load_lds_dwordx4 v208, s[26:27]
	s_add_u32 s100, s26, s58
	s_addc_u32 s101, s27, s59
	s_mov_b32 m0, s37
	s_nop 0
	global_load_lds_dwordx4 v210, s[26:27]
	s_barrier
	s_waitcnt lgkmcnt(0)
	v_mfma_f32_16x16x32_bf16 v[60:63], v[128:131], v[144:147], v[60:63]
	v_mfma_f32_16x16x32_bf16 v[60:63], v[132:135], v[148:151], v[60:63]
	v_mfma_f32_16x16x32_bf16 v[44:47], v[128:131], v[152:155], v[44:47]
	v_mfma_f32_16x16x32_bf16 v[44:47], v[132:135], v[156:159], v[44:47]
	v_mfma_f32_16x16x32_bf16 v[28:31], v[128:131], v[160:163], v[28:31]
	v_mfma_f32_16x16x32_bf16 v[28:31], v[132:135], v[164:167], v[28:31]
	v_mfma_f32_16x16x32_bf16 v[16:19], v[128:131], v[168:171], v[16:19]
	v_mfma_f32_16x16x32_bf16 v[16:19], v[132:135], v[172:175], v[16:19]
	v_mfma_f32_16x16x32_bf16 v[8:11], v[136:139], v[168:171], v[8:11]
	v_mfma_f32_16x16x32_bf16 v[8:11], v[140:143], v[172:175], v[8:11]
	v_mfma_f32_16x16x32_bf16 v[24:27], v[136:139], v[160:163], v[24:27]
	v_mfma_f32_16x16x32_bf16 v[24:27], v[140:143], v[164:167], v[24:27]
	v_mfma_f32_16x16x32_bf16 v[40:43], v[136:139], v[152:155], v[40:43]
	v_mfma_f32_16x16x32_bf16 v[40:43], v[140:143], v[156:159], v[40:43]
	v_mfma_f32_16x16x32_bf16 v[56:59], v[136:139], v[144:147], v[56:59]
	v_mfma_f32_16x16x32_bf16 v[56:59], v[140:143], v[148:151], v[56:59]
	s_barrier
	s_add_u32 s50, s24, 0x40000
	s_addc_u32 s51, s25, 0
	s_add_i32 s47, s52, s36
	s_mov_b32 m0, s47
	s_nop 0
	global_load_lds_dwordx4 v184, s[50:51]
	s_add_i32 m0, s47, 0x2000
	s_nop 0
	global_load_lds_dwordx4 v212, s[50:51]
	s_waitcnt vmcnt(6)
	s_barrier
; #define PG8_STAGE(bufoff, gbase, voff) do { _Pragma("unroll") for (int _i = 0; _i < 2; ++_i) \
;         __builtin_amdgcn_global_load_lds((const unsigned*)((const char*)(gbase) + (voff)[_i]), (LAS unsigned*)(lds + (bufoff) + ldsw + _i * 8192), 16, 0, 0); } while (0)
; #define PG8_LDA(dst, b, h) do { _Pragma("unroll") for (int m = 0; m < 4; ++m) _Pragma("unroll") for (int k = 0; k < 2; ++k) dst[m][k] = *(const LAS bf16x8*)(lds + PG8_SA(b, h) + aoff + m * 2048 + k * 1024); } while (0)
; #define PG8_LDB(dst, b, h) do { _Pragma("unroll") for (int n = 0; n < 2; ++n) _Pragma("unroll") for (int k = 0; k < 2; ++k) dst[n][k] = *(const LAS bf16x8*)(lds + PG8_SB(b, h) + boff + n * 2048 + k * 1024); } while (0)
; #define PG8_MMA(ai, bj, At, Bt) do { __builtin_amdgcn_s_setprio(1); _Pragma("unroll") for (int m = 0; m < 4; ++m) _Pragma("unroll") for (int n = 0; n < 2; ++n) _Pragma("unroll") for (int k = 0; k < 2; ++k) \
;         acc[ai][bj][m][n] = __builtin_amdgcn_mfma_f32_16x16x32_bf16(Bt[n][k], At[m][k], acc[ai][bj][m][n], 0, 0, 0); __builtin_amdgcn_s_setprio(0); } while (0)
; #define PG8_WAIT_V(n) asm volatile("s_waitcnt vmcnt(" #n ")" ::: "memory")
; #define PG8_WAIT_L(n) asm volatile("s_waitcnt lgkmcnt(" #n ")" ::: "memory")
; #define PG8_BAR __builtin_amdgcn_s_barrier()
; #define PG8_SCHED __builtin_amdgcn_sched_barrier(0)
; template <class Epi>
; __device__ __forceinline__ void gemm_phase(LAS unsigned char* lds, const Gemm g, const StaticOrder& S, const Epi& E) {
;     ...
;             PG8_WAIT_V(6); PG8_BAR; PG8_MMA(1, 1, At, B1); PG8_BAR;
;             PG8_LDB(B0, 1, 0); PG8_SCHED; PG8_LDA(At, 1, 0); PG8_STAGE(PG8_SA(0, 1), a2 + hstep, voffA);
;             PG8_WAIT_L(8); PG8_BAR; PG8_WAIT_L(0); PG8_MMA(0, 0, At, B0); PG8_BAR; PG8_SCHED;
;             PG8_LDB(B1, 1, 1); PG8_STAGE(PG8_SB(1, 0), b3, voffB);
;             PG8_BAR; PG8_WAIT_L(0); PG8_MMA(0, 1, At, B1); PG8_BAR;
;             PG8_LDA(At, 1, 1); PG8_STAGE(PG8_SA(1, 0), a3, voffA);
;             PG8_BAR; PG8_WAIT_L(0); PG8_MMA(1, 0, At, B0); PG8_BAR; PG8_SCHED;
	v_mfma_f32_16x16x32_bf16 v[52:55], v[176:179], v[144:147], v[52:55]
	v_mfma_f32_16x16x32_bf16 v[52:55], v[180:183], v[148:151], v[52:55]
	v_mfma_f32_16x16x32_bf16 v[36:39], v[176:179], v[152:155], v[36:39]
	v_mfma_f32_16x16x32_bf16 v[36:39], v[180:183], v[156:159], v[36:39]
	v_mfma_f32_16x16x32_bf16 v[20:23], v[176:179], v[160:163], v[20:23]
	v_mfma_f32_16x16x32_bf16 v[20:23], v[180:183], v[164:167], v[20:23]
	v_mfma_f32_16x16x32_bf16 v[4:7], v[176:179], v[168:171], v[4:7]
	v_mfma_f32_16x16x32_bf16 v[4:7], v[180:183], v[172:175], v[4:7]
	v_mfma_f32_16x16x32_bf16 v[0:3], v[204:207], v[168:171], v[0:3]
	v_mfma_f32_16x16x32_bf16 v[0:3], v[218:221], v[172:175], v[0:3]
	v_mfma_f32_16x16x32_bf16 v[12:15], v[204:207], v[160:163], v[12:15]
	v_mfma_f32_16x16x32_bf16 v[12:15], v[218:221], v[164:167], v[12:15]
	v_mfma_f32_16x16x32_bf16 v[32:35], v[204:207], v[152:155], v[32:35]
	v_mfma_f32_16x16x32_bf16 v[32:35], v[218:221], v[156:159], v[32:35]
	v_mfma_f32_16x16x32_bf16 v[48:51], v[204:207], v[144:147], v[48:51]
	v_mfma_f32_16x16x32_bf16 v[48:51], v[218:221], v[148:151], v[48:51]
	s_add_i32 s47, 0, 0x18000
	s_barrier
	ds_read_b128 v[128:131], v247 offset:32768
	ds_read_b128 v[132:135], v247 offset:33792
	ds_read_b128 v[136:139], v247 offset:34816
	ds_read_b128 v[140:143], v247 offset:35840
	s_add_u32 s26, s26, 0x40000
	s_addc_u32 s27, s27, 0
	s_mov_b32 m0, s38
	ds_read_b128 v[144:147], v249 offset:32768
	ds_read_b128 v[148:151], v249 offset:33792
	ds_read_b128 v[152:155], v249 offset:34816
	ds_read_b128 v[156:159], v249 offset:35840
	ds_read_b128 v[160:163], v249 offset:36864
	ds_read_b128 v[164:167], v249 offset:37888
	ds_read_b128 v[168:171], v249 offset:38912
	ds_read_b128 v[172:175], v249 offset:39936
	global_load_lds_dwordx4 v208, s[26:27]
	s_mov_b32 m0, s39
	s_nop 0
	global_load_lds_dwordx4 v210, s[26:27]
	s_waitcnt lgkmcnt(8)
	s_barrier
	s_waitcnt lgkmcnt(0)
	v_mfma_f32_16x16x32_bf16 v[124:127], v[128:131], v[144:147], v[124:127]
	v_mfma_f32_16x16x32_bf16 v[124:127], v[132:135], v[148:151], v[124:127]
	v_mfma_f32_16x16x32_bf16 v[108:111], v[128:131], v[152:155], v[108:111]
	v_mfma_f32_16x16x32_bf16 v[108:111], v[132:135], v[156:159], v[108:111]
	v_mfma_f32_16x16x32_bf16 v[92:95], v[128:131], v[160:163], v[92:95]
	v_mfma_f32_16x16x32_bf16 v[92:95], v[132:135], v[164:167], v[92:95]
	v_mfma_f32_16x16x32_bf16 v[76:79], v[128:131], v[168:171], v[76:79]
	v_mfma_f32_16x16x32_bf16 v[76:79], v[132:135], v[172:175], v[76:79]
	v_mfma_f32_16x16x32_bf16 v[72:75], v[136:139], v[168:171], v[72:75]
	v_mfma_f32_16x16x32_bf16 v[72:75], v[140:143], v[172:175], v[72:75]
	v_mfma_f32_16x16x32_bf16 v[88:91], v[136:139], v[160:163], v[88:91]
	v_mfma_f32_16x16x32_bf16 v[88:91], v[140:143], v[164:167], v[88:91]
	v_mfma_f32_16x16x32_bf16 v[104:107], v[136:139], v[152:155], v[104:107]
	v_mfma_f32_16x16x32_bf16 v[104:107], v[140:143], v[156:159], v[104:107]
	v_mfma_f32_16x16x32_bf16 v[120:123], v[136:139], v[144:147], v[120:123]
	v_mfma_f32_16x16x32_bf16 v[120:123], v[140:143], v[148:151], v[120:123]
	s_barrier
	s_add_i32 s26, 0, 0x1c000
	s_add_i32 s27, s47, s36
	s_mov_b32 m0, s27
	ds_read_b128 v[176:179], v247 offset:49152
	ds_read_b128 v[180:183], v247 offset:50176
	ds_read_b128 v[204:207], v247 offset:51200
	ds_read_b128 v[218:221], v247 offset:52224
	global_load_lds_dwordx4 v184, s[98:99]
	s_add_i32 m0, s27, 0x2000
	s_nop 0
	global_load_lds_dwordx4 v212, s[98:99]
	s_barrier
	s_waitcnt lgkmcnt(0)
	v_mfma_f32_16x16x32_bf16 v[116:119], v[176:179], v[144:147], v[116:119]
	v_mfma_f32_16x16x32_bf16 v[116:119], v[180:183], v[148:151], v[116:119]
	v_mfma_f32_16x16x32_bf16 v[100:103], v[176:179], v[152:155], v[100:103]
	v_mfma_f32_16x16x32_bf16 v[100:103], v[180:183], v[156:159], v[100:103]
	v_mfma_f32_16x16x32_bf16 v[84:87], v[176:179], v[160:163], v[84:87]
	v_mfma_f32_16x16x32_bf16 v[84:87], v[180:183], v[164:167], v[84:87]
	v_mfma_f32_16x16x32_bf16 v[68:71], v[176:179], v[168:171], v[68:71]
	v_mfma_f32_16x16x32_bf16 v[68:71], v[180:183], v[172:175], v[68:71]
	v_mfma_f32_16x16x32_bf16 v[64:67], v[204:207], v[168:171], v[64:67]
	v_mfma_f32_16x16x32_bf16 v[64:67], v[218:221], v[172:175], v[64:67]
	v_mfma_f32_16x16x32_bf16 v[80:83], v[204:207], v[160:163], v[80:83]
	v_mfma_f32_16x16x32_bf16 v[80:83], v[218:221], v[164:167], v[80:83]
	v_mfma_f32_16x16x32_bf16 v[96:99], v[204:207], v[152:155], v[96:99]
	v_mfma_f32_16x16x32_bf16 v[96:99], v[218:221], v[156:159], v[96:99]
	v_mfma_f32_16x16x32_bf16 v[112:115], v[204:207], v[144:147], v[112:115]
	v_mfma_f32_16x16x32_bf16 v[112:115], v[218:221], v[148:151], v[112:115]
	s_mov_b32 m0, s41
	s_barrier
; #define PG8_STAGE(bufoff, gbase, voff) do { _Pragma("unroll") for (int _i = 0; _i < 2; ++_i) \
;         __builtin_amdgcn_global_load_lds((const unsigned*)((const char*)(gbase) + (voff)[_i]), (LAS unsigned*)(lds + (bufoff) + ldsw + _i * 8192), 16, 0, 0); } while (0)
; #define PG8_MMA(ai, bj, At, Bt) do { __builtin_amdgcn_s_setprio(1); _Pragma("unroll") for (int m = 0; m < 4; ++m) _Pragma("unroll") for (int n = 0; n < 2; ++n) _Pragma("unroll") for (int k = 0; k < 2; ++k) \
;         acc[ai][bj][m][n] = __builtin_amdgcn_mfma_f32_16x16x32_bf16(Bt[n][k], At[m][k], acc[ai][bj][m][n], 0, 0, 0); __builtin_amdgcn_s_setprio(0); } while (0)
; #define PG8_WAIT_V(n) asm volatile("s_waitcnt vmcnt(" #n ")" ::: "memory")
; #define PG8_WAIT_L(n) asm volatile("s_waitcnt lgkmcnt(" #n ")" ::: "memory")
; #define PG8_BAR __builtin_amdgcn_s_barrier()
; #define PG8_SCHED __builtin_amdgcn_sched_barrier(0)
; template <class Epi>
; __device__ __forceinline__ void gemm_phase(LAS unsigned char* lds, const Gemm g, const StaticOrder& S, const Epi& E) {
;     ...
;             PG8_BAR; PG8_WAIT_L(0); PG8_MMA(1, 0, At, B0); PG8_BAR; PG8_SCHED;
;             PG8_STAGE(PG8_SB(1, 1), b3 + hstep, voffB);
;             PG8_WAIT_V(6); PG8_BAR; PG8_MMA(1, 1, At, B1); PG8_BAR;
;         }
;     __device__ __forceinline__ void operator()(const Acc& acc, const Unit& u, int wr, int wc, int fr, int fq) const {
;         const int row0 = u.pm * 256 + wr * 64 + fr, col0 = u.pn * 256 + wc * 32 + 8 * fq;
;         const bf16_t* __restrict__ gp = gate; bf16_t* __restrict__ mg = merged;
;         u32x4 gw[4][2], pw[2][2];
; #pragma unroll
;         for (int gidx = 0; gidx < 4; ++gidx)
; #pragma unroll
;             for (int bj = 0; bj < 2; ++bj) gw[gidx][bj] = *(const u32x4*)(gp + (size_t)(row0 + gidx * 16) * 4096 + col0 + bj * 128);
; #pragma unroll
;         for (int bj = 0; bj < 2; ++bj) pw[0][bj] = accum ? *(const u32x4*)(mg + (size_t)row0 * 2048 + col0 + bj * 128) : (u32x4){0u, 0u, 0u, 0u};
	ds_read_b128 v[144:147], v249 offset:49152
	ds_read_b128 v[148:151], v249 offset:50176
	ds_read_b128 v[152:155], v249 offset:51200
	ds_read_b128 v[156:159], v249 offset:52224
	ds_read_b128 v[160:163], v249 offset:53248
	ds_read_b128 v[164:167], v249 offset:54272
	ds_read_b128 v[168:171], v249 offset:55296
	ds_read_b128 v[172:175], v249 offset:56320
	global_load_lds_dwordx4 v208, s[100:101]
	s_mov_b32 m0, s42
	s_nop 0
	global_load_lds_dwordx4 v210, s[100:101]
	s_barrier
	s_waitcnt lgkmcnt(0)
	v_mfma_f32_16x16x32_bf16 v[60:63], v[128:131], v[144:147], v[60:63]
	v_mfma_f32_16x16x32_bf16 v[60:63], v[132:135], v[148:151], v[60:63]
	v_mfma_f32_16x16x32_bf16 v[44:47], v[128:131], v[152:155], v[44:47]
	v_mfma_f32_16x16x32_bf16 v[44:47], v[132:135], v[156:159], v[44:47]
	v_mfma_f32_16x16x32_bf16 v[28:31], v[128:131], v[160:163], v[28:31]
	v_mfma_f32_16x16x32_bf16 v[28:31], v[132:135], v[164:167], v[28:31]
	v_mfma_f32_16x16x32_bf16 v[16:19], v[128:131], v[168:171], v[16:19]
	v_mfma_f32_16x16x32_bf16 v[16:19], v[132:135], v[172:175], v[16:19]
	v_mfma_f32_16x16x32_bf16 v[8:11], v[136:139], v[168:171], v[8:11]
	v_mfma_f32_16x16x32_bf16 v[8:11], v[140:143], v[172:175], v[8:11]
	v_mfma_f32_16x16x32_bf16 v[24:27], v[136:139], v[160:163], v[24:27]
	v_mfma_f32_16x16x32_bf16 v[24:27], v[140:143], v[164:167], v[24:27]
	v_mfma_f32_16x16x32_bf16 v[40:43], v[136:139], v[152:155], v[40:43]
	v_mfma_f32_16x16x32_bf16 v[40:43], v[140:143], v[156:159], v[40:43]
	v_mfma_f32_16x16x32_bf16 v[56:59], v[136:139], v[144:147], v[56:59]
	v_mfma_f32_16x16x32_bf16 v[56:59], v[140:143], v[148:151], v[56:59]
	s_barrier
	s_add_u32 s24, s24, 0x40080
	s_addc_u32 s25, s25, 0
	s_add_i32 s26, s26, s36
	s_mov_b32 m0, s26
	s_nop 0
	global_load_lds_dwordx4 v184, s[24:25]
	s_add_i32 m0, s26, 0x2000
	s_nop 0
	global_load_lds_dwordx4 v212, s[24:25]
	s_waitcnt vmcnt(6)
	s_barrier
	v_mfma_f32_16x16x32_bf16 v[52:55], v[176:179], v[144:147], v[52:55]
	v_mfma_f32_16x16x32_bf16 v[52:55], v[180:183], v[148:151], v[52:55]
	v_mfma_f32_16x16x32_bf16 v[36:39], v[176:179], v[152:155], v[36:39]
	v_mfma_f32_16x16x32_bf16 v[36:39], v[180:183], v[156:159], v[36:39]
	v_mfma_f32_16x16x32_bf16 v[20:23], v[176:179], v[160:163], v[20:23]
	v_mfma_f32_16x16x32_bf16 v[20:23], v[180:183], v[164:167], v[20:23]
	v_mfma_f32_16x16x32_bf16 v[4:7], v[176:179], v[168:171], v[4:7]
	v_mfma_f32_16x16x32_bf16 v[4:7], v[180:183], v[172:175], v[4:7]
	v_mfma_f32_16x16x32_bf16 v[0:3], v[204:207], v[168:171], v[0:3]
	v_mfma_f32_16x16x32_bf16 v[0:3], v[218:221], v[172:175], v[0:3]
	v_mfma_f32_16x16x32_bf16 v[12:15], v[204:207], v[160:163], v[12:15]
	v_mfma_f32_16x16x32_bf16 v[12:15], v[218:221], v[164:167], v[12:15]
	v_mfma_f32_16x16x32_bf16 v[32:35], v[204:207], v[152:155], v[32:35]
	v_mfma_f32_16x16x32_bf16 v[32:35], v[218:221], v[156:159], v[32:35]
	v_mfma_f32_16x16x32_bf16 v[48:51], v[204:207], v[144:147], v[48:51]
	v_mfma_f32_16x16x32_bf16 v[48:51], v[218:221], v[148:151], v[48:51]
	s_add_i32 s46, s46, 2
	s_add_u32 s22, s22, 0x100
	s_addc_u32 s23, s23, 0
	s_add_u32 s43, s43, 0x100
	s_addc_u32 s45, s45, 0
	s_cmp_gt_u32 s46, 13
	s_barrier
	s_cbranch_scc0 .LBB0_43
	v_lshl_or_b32 v128, s8, 8, v248
	v_lshl_add_u32 v222, s20, 8, v187
	v_ashrrev_i32_e32 v129, 31, v128
	v_lshlrev_b64 v[136:137], 1, v[128:129]
	v_ashrrev_i32_e32 v223, 31, v222
	v_lshl_add_u64 v[224:225], s[10:11], 0, v[136:137]
	v_lshlrev_b64 v[130:131], 13, v[222:223]
	v_lshl_add_u64 v[130:131], v[224:225], 0, v[130:131]
	global_load_dwordx4 v[176:179], v[130:131], off
	global_load_dwordx4 v[168:171], v[130:131], off offset:256
	v_or_b32_e32 v130, 16, v222
	v_ashrrev_i32_e32 v131, 31, v130
	v_lshlrev_b64 v[132:133], 13, v[130:131]
	v_or_b32_e32 v230, 32, v222
	v_lshl_add_u64 v[132:133], v[224:225], 0, v[132:133]
	v_ashrrev_i32_e32 v231, 31, v230
	global_load_dwordx4 v[156:159], v[132:133], off
	global_load_dwordx4 v[152:155], v[132:133], off offset:256
	v_lshlrev_b64 v[132:133], 13, v[230:231]
	v_or_b32_e32 v226, 48, v222
	v_lshl_add_u64 v[132:133], v[224:225], 0, v[132:133]
	v_ashrrev_i32_e32 v227, 31, v226
	global_load_dwordx4 v[148:151], v[132:133], off
	global_load_dwordx4 v[144:147], v[132:133], off offset:256
	v_lshlrev_b64 v[132:133], 13, v[226:227]
	v_lshl_add_u64 v[132:133], v[224:225], 0, v[132:133]
	global_load_dwordx4 v[140:143], v[132:133], off
	s_nop 0
	global_load_dwordx4 v[132:135], v[132:133], off offset:256
	v_lshlrev_b64 v[232:233], 12, v[222:223]
	v_lshl_add_u64 v[138:139], s[66:67], 0, v[232:233]
	v_lshl_add_u64 v[136:137], v[138:139], 0, v[136:137]
	v_cndmask_b32_e64 v138, 0, 1, s[0:1]
	v_mov_b32_e32 v172, 0
	v_cmp_ne_u32_e64 s[8:9], 1, v138
	s_andn2_b64 vcc, exec, s[0:1]
	v_mov_b32_e32 v180, 0
	v_mov_b32_e32 v181, 0
	v_mov_b32_e32 v182, 0
	v_mov_b32_e32 v183, 0
	s_cbranch_vccnz .LBB0_46
	global_load_dwordx4 v[180:183], v[136:137], off

; #define PG8_STAGE(bufoff, gbase, voff) do { _Pragma("unroll") for (int _i = 0; _i < 2; ++_i) \
;         __builtin_amdgcn_global_load_lds((const unsigned*)((const char*)(gbase) + (voff)[_i]), (LAS unsigned*)(lds + (bufoff) + ldsw + _i * 8192), 16, 0, 0); } while (0)
; #define PG8_LDA(dst, b, h) do { _Pragma("unroll") for (int m = 0; m < 4; ++m) _Pragma("unroll") for (int k = 0; k < 2; ++k) dst[m][k] = *(const LAS bf16x8*)(lds + PG8_SA(b, h) + aoff + m * 2048 + k * 1024); } while (0)
; #define PG8_LDB(dst, b, h) do { _Pragma("unroll") for (int n = 0; n < 2; ++n) _Pragma("unroll") for (int k = 0; k < 2; ++k) dst[n][k] = *(const LAS bf16x8*)(lds + PG8_SB(b, h) + boff + n * 2048 + k * 1024); } while (0)
; #define PG8_MMA(ai, bj, At, Bt) do { __builtin_amdgcn_s_setprio(1); _Pragma("unroll") for (int m = 0; m < 4; ++m) _Pragma("unroll") for (int n = 0; n < 2; ++n) _Pragma("unroll") for (int k = 0; k < 2; ++k) \
;         acc[ai][bj][m][n] = __builtin_amdgcn_mfma_f32_16x16x32_bf16(Bt[n][k], At[m][k], acc[ai][bj][m][n], 0, 0, 0); __builtin_amdgcn_s_setprio(0); } while (0)
; #define PG8_WAIT_V(n) asm volatile("s_waitcnt vmcnt(" #n ")" ::: "memory")
; #define PG8_WAIT_L(n) asm volatile("s_waitcnt lgkmcnt(" #n ")" ::: "memory")
; template <class Epi>
; __device__ __forceinline__ void gemm_phase(LAS unsigned char* lds, const Gemm g, const StaticOrder& S, const Epi& E) {
;     ...
;         for (int t = 0; t < nt; t += 2) {
;             const bool last = (t == nt - 2);
;             const char* a1 = cA + (size_t)(t + 1) * kstep;
;             const char* a2 = last ? nA : cA + (size_t)(t + 2) * kstep; const char* b2 = last ? nB : cB + (size_t)(t + 2) * kstep;
;             const char* a3 = a2 + kstep; const char* b3 = b2 + kstep;
;             PG8_LDB(B0, 0, 0); PG8_SCHED; PG8_LDA(At, 0, 0); PG8_STAGE(PG8_SA(1, 1), a1 + hstep, voffA);
;             PG8_WAIT_L(8); PG8_BAR; PG8_WAIT_L(0); PG8_MMA(0, 0, At, B0); PG8_BAR; PG8_SCHED;
;             PG8_LDB(B1, 0, 1); PG8_STAGE(PG8_SB(0, 0), b2, voffB);
;             PG8_BAR; PG8_WAIT_L(0); PG8_MMA(0, 1, At, B1); PG8_BAR;
;             PG8_LDA(At, 0, 1); PG8_STAGE(PG8_SA(0, 0), a2, voffA);
;             PG8_BAR; PG8_WAIT_L(0); PG8_MMA(1, 0, At, B0); PG8_BAR; PG8_SCHED;
;             PG8_STAGE(PG8_SB(0, 1), b2 + hstep, voffB);
;             PG8_WAIT_V(6); PG8_BAR; PG8_MMA(1, 1, At, B1); PG8_BAR;
.LBB0_366:
	s_add_u32 s28, s26, 0xfff80080
	s_addc_u32 s29, s27, -1
	s_add_i32 s47, 0, 0x10000
	ds_read_b128 v[138:141], v143
	ds_read_b128 v[146:149], v143 offset:1024
	ds_read_b128 v[150:153], v143 offset:2048
	ds_read_b128 v[154:157], v143 offset:3072
	s_cmp_eq_u32 s43, 28
	s_cselect_b32 s31, s3, s29
	s_cselect_b32 s30, s9, s28
	s_cselect_b32 s29, s1, s35
	s_cselect_b32 s28, s19, s34
	s_add_i32 m0, s25, 0xc000
	ds_read_b128 v[158:161], v145
	ds_read_b128 v[162:165], v145 offset:1024
	ds_read_b128 v[166:169], v145 offset:2048
	ds_read_b128 v[170:173], v145 offset:3072
	ds_read_b128 v[174:177], v145 offset:4096
	ds_read_b128 v[178:181], v145 offset:5120
	ds_read_b128 v[204:207], v145 offset:6144
	ds_read_b128 v[208:211], v145 offset:7168
	global_load_lds_dwordx4 v134, s[26:27]
	s_add_i32 m0, s25, 0xe000
	s_nop 0
	global_load_lds_dwordx4 v136, s[26:27]
	s_waitcnt lgkmcnt(8)
	s_barrier
	s_waitcnt lgkmcnt(0)
	v_mfma_f32_16x16x32_bf16 v[124:127], v[138:141], v[158:161], v[124:127]
	v_mfma_f32_16x16x32_bf16 v[124:127], v[146:149], v[162:165], v[124:127]
	v_mfma_f32_16x16x32_bf16 v[108:111], v[138:141], v[166:169], v[108:111]
	v_mfma_f32_16x16x32_bf16 v[108:111], v[146:149], v[170:173], v[108:111]
	v_mfma_f32_16x16x32_bf16 v[92:95], v[138:141], v[174:177], v[92:95]
	v_mfma_f32_16x16x32_bf16 v[92:95], v[146:149], v[178:181], v[92:95]
	v_mfma_f32_16x16x32_bf16 v[76:79], v[138:141], v[204:207], v[76:79]
	v_mfma_f32_16x16x32_bf16 v[76:79], v[146:149], v[208:211], v[76:79]
	v_mfma_f32_16x16x32_bf16 v[72:75], v[150:153], v[204:207], v[72:75]
	v_mfma_f32_16x16x32_bf16 v[72:75], v[154:157], v[208:211], v[72:75]
	v_mfma_f32_16x16x32_bf16 v[88:91], v[150:153], v[174:177], v[88:91]
	v_mfma_f32_16x16x32_bf16 v[88:91], v[154:157], v[178:181], v[88:91]
	v_mfma_f32_16x16x32_bf16 v[104:107], v[150:153], v[166:169], v[104:107]
	v_mfma_f32_16x16x32_bf16 v[104:107], v[154:157], v[170:173], v[104:107]
	v_mfma_f32_16x16x32_bf16 v[120:123], v[150:153], v[158:161], v[120:123]
	v_mfma_f32_16x16x32_bf16 v[120:123], v[154:157], v[162:165], v[120:123]
	s_barrier
	s_add_i32 s52, 0, 0x14000
	s_add_i32 s47, s47, s38
	ds_read_b128 v[212:215], v143 offset:16384
	ds_read_b128 v[216:219], v143 offset:17408
	ds_read_b128 v[220:223], v143 offset:18432
	ds_read_b128 v[224:227], v143 offset:19456
	s_mov_b32 m0, s47
	s_add_u32 s98, s28, s58
	s_addc_u32 s99, s29, s59
	global_load_lds_dwordx4 v184, s[28:29]
	s_add_i32 m0, s47, 0x2000
	s_nop 0
	global_load_lds_dwordx4 v132, s[28:29]
	s_barrier
	s_waitcnt lgkmcnt(0)
	v_mfma_f32_16x16x32_bf16 v[116:119], v[212:215], v[158:161], v[116:119]
	v_mfma_f32_16x16x32_bf16 v[116:119], v[216:219], v[162:165], v[116:119]
	v_mfma_f32_16x16x32_bf16 v[100:103], v[212:215], v[166:169], v[100:103]
	v_mfma_f32_16x16x32_bf16 v[100:103], v[216:219], v[170:173], v[100:103]
	v_mfma_f32_16x16x32_bf16 v[84:87], v[212:215], v[174:177], v[84:87]
	v_mfma_f32_16x16x32_bf16 v[84:87], v[216:219], v[178:181], v[84:87]
	v_mfma_f32_16x16x32_bf16 v[68:71], v[212:215], v[204:207], v[68:71]
	v_mfma_f32_16x16x32_bf16 v[68:71], v[216:219], v[208:211], v[68:71]
	v_mfma_f32_16x16x32_bf16 v[64:67], v[220:223], v[204:207], v[64:67]
	v_mfma_f32_16x16x32_bf16 v[64:67], v[224:227], v[208:211], v[64:67]
	v_mfma_f32_16x16x32_bf16 v[80:83], v[220:223], v[174:177], v[80:83]
	v_mfma_f32_16x16x32_bf16 v[80:83], v[224:227], v[178:181], v[80:83]
	v_mfma_f32_16x16x32_bf16 v[96:99], v[220:223], v[166:169], v[96:99]
	v_mfma_f32_16x16x32_bf16 v[96:99], v[224:227], v[170:173], v[96:99]
	v_mfma_f32_16x16x32_bf16 v[112:115], v[220:223], v[158:161], v[112:115]
	v_mfma_f32_16x16x32_bf16 v[112:115], v[224:227], v[162:165], v[112:115]
	s_mov_b32 m0, s25
	s_barrier
	ds_read_b128 v[158:161], v145 offset:16384
	ds_read_b128 v[162:165], v145 offset:17408
	ds_read_b128 v[166:169], v145 offset:18432
	ds_read_b128 v[170:173], v145 offset:19456
	ds_read_b128 v[174:177], v145 offset:20480
	ds_read_b128 v[178:181], v145 offset:21504
	ds_read_b128 v[204:207], v145 offset:22528
	ds_read_b128 v[208:211], v145 offset:23552
	global_load_lds_dwordx4 v128, s[30:31]
	s_add_u32 s100, s30, s58
	s_addc_u32 s101, s31, s59
	s_mov_b32 m0, s39
	s_nop 0
	global_load_lds_dwordx4 v130, s[30:31]
	s_barrier
	s_waitcnt lgkmcnt(0)
	v_mfma_f32_16x16x32_bf16 v[60:63], v[138:141], v[158:161], v[60:63]
	v_mfma_f32_16x16x32_bf16 v[60:63], v[146:149], v[162:165], v[60:63]
	v_mfma_f32_16x16x32_bf16 v[44:47], v[138:141], v[166:169], v[44:47]
	v_mfma_f32_16x16x32_bf16 v[44:47], v[146:149], v[170:173], v[44:47]
	v_mfma_f32_16x16x32_bf16 v[28:31], v[138:141], v[174:177], v[28:31]
	v_mfma_f32_16x16x32_bf16 v[28:31], v[146:149], v[178:181], v[28:31]
	v_mfma_f32_16x16x32_bf16 v[12:15], v[138:141], v[204:207], v[12:15]
	v_mfma_f32_16x16x32_bf16 v[12:15], v[146:149], v[208:211], v[12:15]
	v_mfma_f32_16x16x32_bf16 v[8:11], v[150:153], v[204:207], v[8:11]
	v_mfma_f32_16x16x32_bf16 v[8:11], v[154:157], v[208:211], v[8:11]
	v_mfma_f32_16x16x32_bf16 v[24:27], v[150:153], v[174:177], v[24:27]
	v_mfma_f32_16x16x32_bf16 v[24:27], v[154:157], v[178:181], v[24:27]
	v_mfma_f32_16x16x32_bf16 v[40:43], v[150:153], v[166:169], v[40:43]
	v_mfma_f32_16x16x32_bf16 v[40:43], v[154:157], v[170:173], v[40:43]
	v_mfma_f32_16x16x32_bf16 v[56:59], v[150:153], v[158:161], v[56:59]
	v_mfma_f32_16x16x32_bf16 v[56:59], v[154:157], v[162:165], v[56:59]
	s_barrier
	s_add_u32 s50, s28, 0x80000
	s_addc_u32 s51, s29, 0
	s_add_i32 s47, s52, s38
	s_mov_b32 m0, s47
	s_nop 0
	global_load_lds_dwordx4 v184, s[50:51]
	s_add_i32 m0, s47, 0x2000
	s_nop 0
	global_load_lds_dwordx4 v132, s[50:51]
	s_waitcnt vmcnt(6)
	s_barrier
; #define PG8_STAGE(bufoff, gbase, voff) do { _Pragma("unroll") for (int _i = 0; _i < 2; ++_i) \
;         __builtin_amdgcn_global_load_lds((const unsigned*)((const char*)(gbase) + (voff)[_i]), (LAS unsigned*)(lds + (bufoff) + ldsw + _i * 8192), 16, 0, 0); } while (0)
; #define PG8_LDA(dst, b, h) do { _Pragma("unroll") for (int m = 0; m < 4; ++m) _Pragma("unroll") for (int k = 0; k < 2; ++k) dst[m][k] = *(const LAS bf16x8*)(lds + PG8_SA(b, h) + aoff + m * 2048 + k * 1024); } while (0)
; #define PG8_LDB(dst, b, h) do { _Pragma("unroll") for (int n = 0; n < 2; ++n) _Pragma("unroll") for (int k = 0; k < 2; ++k) dst[n][k] = *(const LAS bf16x8*)(lds + PG8_SB(b, h) + boff + n * 2048 + k * 1024); } while (0)
; #define PG8_MMA(ai, bj, At, Bt) do { __builtin_amdgcn_s_setprio(1); _Pragma("unroll") for (int m = 0; m < 4; ++m) _Pragma("unroll") for (int n = 0; n < 2; ++n) _Pragma("unroll") for (int k = 0; k < 2; ++k) \
;         acc[ai][bj][m][n] = __builtin_amdgcn_mfma_f32_16x16x32_bf16(Bt[n][k], At[m][k], acc[ai][bj][m][n], 0, 0, 0); __builtin_amdgcn_s_setprio(0); } while (0)
; #define PG8_WAIT_V(n) asm volatile("s_waitcnt vmcnt(" #n ")" ::: "memory")
; #define PG8_WAIT_L(n) asm volatile("s_waitcnt lgkmcnt(" #n ")" ::: "memory")
; #define PG8_BAR __builtin_amdgcn_s_barrier()
; #define PG8_SCHED __builtin_amdgcn_sched_barrier(0)
; template <class Epi>
; __device__ __forceinline__ void gemm_phase(LAS unsigned char* lds, const Gemm g, const StaticOrder& S, const Epi& E) {
;     ...
;             PG8_WAIT_V(6); PG8_BAR; PG8_MMA(1, 1, At, B1); PG8_BAR;
;             PG8_LDB(B0, 1, 0); PG8_SCHED; PG8_LDA(At, 1, 0); PG8_STAGE(PG8_SA(0, 1), a2 + hstep, voffA);
;             PG8_WAIT_L(8); PG8_BAR; PG8_WAIT_L(0); PG8_MMA(0, 0, At, B0); PG8_BAR; PG8_SCHED;
;             PG8_LDB(B1, 1, 1); PG8_STAGE(PG8_SB(1, 0), b3, voffB);
;             PG8_BAR; PG8_WAIT_L(0); PG8_MMA(0, 1, At, B1); PG8_BAR;
;             PG8_LDA(At, 1, 1); PG8_STAGE(PG8_SA(1, 0), a3, voffA);
;             PG8_BAR; PG8_WAIT_L(0); PG8_MMA(1, 0, At, B0); PG8_BAR; PG8_SCHED;
	v_mfma_f32_16x16x32_bf16 v[52:55], v[212:215], v[158:161], v[52:55]
	v_mfma_f32_16x16x32_bf16 v[52:55], v[216:219], v[162:165], v[52:55]
	v_mfma_f32_16x16x32_bf16 v[36:39], v[212:215], v[166:169], v[36:39]
	v_mfma_f32_16x16x32_bf16 v[36:39], v[216:219], v[170:173], v[36:39]
	v_mfma_f32_16x16x32_bf16 v[20:23], v[212:215], v[174:177], v[20:23]
	v_mfma_f32_16x16x32_bf16 v[20:23], v[216:219], v[178:181], v[20:23]
	v_mfma_f32_16x16x32_bf16 v[4:7], v[212:215], v[204:207], v[4:7]
	v_mfma_f32_16x16x32_bf16 v[4:7], v[216:219], v[208:211], v[4:7]
	v_mfma_f32_16x16x32_bf16 v[0:3], v[220:223], v[204:207], v[0:3]
	v_mfma_f32_16x16x32_bf16 v[0:3], v[224:227], v[208:211], v[0:3]
	v_mfma_f32_16x16x32_bf16 v[16:19], v[220:223], v[174:177], v[16:19]
	v_mfma_f32_16x16x32_bf16 v[16:19], v[224:227], v[178:181], v[16:19]
	v_mfma_f32_16x16x32_bf16 v[32:35], v[220:223], v[166:169], v[32:35]
	v_mfma_f32_16x16x32_bf16 v[32:35], v[224:227], v[170:173], v[32:35]
	v_mfma_f32_16x16x32_bf16 v[48:51], v[220:223], v[158:161], v[48:51]
	v_mfma_f32_16x16x32_bf16 v[48:51], v[224:227], v[162:165], v[48:51]
	s_add_i32 s47, 0, 0x18000
	s_barrier
	ds_read_b128 v[138:141], v143 offset:32768
	ds_read_b128 v[146:149], v143 offset:33792
	ds_read_b128 v[150:153], v143 offset:34816
	ds_read_b128 v[154:157], v143 offset:35840
	s_add_u32 s30, s30, 0x80000
	s_addc_u32 s31, s31, 0
	s_mov_b32 m0, s40
	ds_read_b128 v[158:161], v145 offset:32768
	ds_read_b128 v[162:165], v145 offset:33792
	ds_read_b128 v[166:169], v145 offset:34816
	ds_read_b128 v[170:173], v145 offset:35840
	ds_read_b128 v[174:177], v145 offset:36864
	ds_read_b128 v[178:181], v145 offset:37888
	ds_read_b128 v[204:207], v145 offset:38912
	ds_read_b128 v[208:211], v145 offset:39936
	global_load_lds_dwordx4 v128, s[30:31]
	s_mov_b32 m0, s41
	s_nop 0
	global_load_lds_dwordx4 v130, s[30:31]
	s_waitcnt lgkmcnt(8)
	s_barrier
	s_waitcnt lgkmcnt(0)
	v_mfma_f32_16x16x32_bf16 v[124:127], v[138:141], v[158:161], v[124:127]
	v_mfma_f32_16x16x32_bf16 v[124:127], v[146:149], v[162:165], v[124:127]
	v_mfma_f32_16x16x32_bf16 v[108:111], v[138:141], v[166:169], v[108:111]
	v_mfma_f32_16x16x32_bf16 v[108:111], v[146:149], v[170:173], v[108:111]
	v_mfma_f32_16x16x32_bf16 v[92:95], v[138:141], v[174:177], v[92:95]
	v_mfma_f32_16x16x32_bf16 v[92:95], v[146:149], v[178:181], v[92:95]
	v_mfma_f32_16x16x32_bf16 v[76:79], v[138:141], v[204:207], v[76:79]
	v_mfma_f32_16x16x32_bf16 v[76:79], v[146:149], v[208:211], v[76:79]
	v_mfma_f32_16x16x32_bf16 v[72:75], v[150:153], v[204:207], v[72:75]
	v_mfma_f32_16x16x32_bf16 v[72:75], v[154:157], v[208:211], v[72:75]
	v_mfma_f32_16x16x32_bf16 v[88:91], v[150:153], v[174:177], v[88:91]
	v_mfma_f32_16x16x32_bf16 v[88:91], v[154:157], v[178:181], v[88:91]
	v_mfma_f32_16x16x32_bf16 v[104:107], v[150:153], v[166:169], v[104:107]
	v_mfma_f32_16x16x32_bf16 v[104:107], v[154:157], v[170:173], v[104:107]
	v_mfma_f32_16x16x32_bf16 v[120:123], v[150:153], v[158:161], v[120:123]
	v_mfma_f32_16x16x32_bf16 v[120:123], v[154:157], v[162:165], v[120:123]
	s_barrier
	s_add_i32 s30, 0, 0x1c000
	s_add_i32 s31, s47, s38
	s_mov_b32 m0, s31
	ds_read_b128 v[212:215], v143 offset:49152
	ds_read_b128 v[216:219], v143 offset:50176
	ds_read_b128 v[220:223], v143 offset:51200
	ds_read_b128 v[224:227], v143 offset:52224
	global_load_lds_dwordx4 v184, s[98:99]
	s_add_i32 m0, s31, 0x2000
	s_nop 0
	global_load_lds_dwordx4 v132, s[98:99]
	s_barrier
	s_waitcnt lgkmcnt(0)
	v_mfma_f32_16x16x32_bf16 v[116:119], v[212:215], v[158:161], v[116:119]
	v_mfma_f32_16x16x32_bf16 v[116:119], v[216:219], v[162:165], v[116:119]
	v_mfma_f32_16x16x32_bf16 v[100:103], v[212:215], v[166:169], v[100:103]
	v_mfma_f32_16x16x32_bf16 v[100:103], v[216:219], v[170:173], v[100:103]
	v_mfma_f32_16x16x32_bf16 v[84:87], v[212:215], v[174:177], v[84:87]
	v_mfma_f32_16x16x32_bf16 v[84:87], v[216:219], v[178:181], v[84:87]
	v_mfma_f32_16x16x32_bf16 v[68:71], v[212:215], v[204:207], v[68:71]
	v_mfma_f32_16x16x32_bf16 v[68:71], v[216:219], v[208:211], v[68:71]
	v_mfma_f32_16x16x32_bf16 v[64:67], v[220:223], v[204:207], v[64:67]
	v_mfma_f32_16x16x32_bf16 v[64:67], v[224:227], v[208:211], v[64:67]
	v_mfma_f32_16x16x32_bf16 v[80:83], v[220:223], v[174:177], v[80:83]
	v_mfma_f32_16x16x32_bf16 v[80:83], v[224:227], v[178:181], v[80:83]
	v_mfma_f32_16x16x32_bf16 v[96:99], v[220:223], v[166:169], v[96:99]
	v_mfma_f32_16x16x32_bf16 v[96:99], v[224:227], v[170:173], v[96:99]
	v_mfma_f32_16x16x32_bf16 v[112:115], v[220:223], v[158:161], v[112:115]
	v_mfma_f32_16x16x32_bf16 v[112:115], v[224:227], v[162:165], v[112:115]
	s_mov_b32 m0, s42
	s_barrier
; #define PG8_STAGE(bufoff, gbase, voff) do { _Pragma("unroll") for (int _i = 0; _i < 2; ++_i) \
;         __builtin_amdgcn_global_load_lds((const unsigned*)((const char*)(gbase) + (voff)[_i]), (LAS unsigned*)(lds + (bufoff) + ldsw + _i * 8192), 16, 0, 0); } while (0)
; #define PG8_LDA(dst, b, h) do { _Pragma("unroll") for (int m = 0; m < 4; ++m) _Pragma("unroll") for (int k = 0; k < 2; ++k) dst[m][k] = *(const LAS bf16x8*)(lds + PG8_SA(b, h) + aoff + m * 2048 + k * 1024); } while (0)
; #define PG8_MMA(ai, bj, At, Bt) do { __builtin_amdgcn_s_setprio(1); _Pragma("unroll") for (int m = 0; m < 4; ++m) _Pragma("unroll") for (int n = 0; n < 2; ++n) _Pragma("unroll") for (int k = 0; k < 2; ++k) \
;         acc[ai][bj][m][n] = __builtin_amdgcn_mfma_f32_16x16x32_bf16(Bt[n][k], At[m][k], acc[ai][bj][m][n], 0, 0, 0); __builtin_amdgcn_s_setprio(0); } while (0)
; #define PG8_WAIT_V(n) asm volatile("s_waitcnt vmcnt(" #n ")" ::: "memory")
; #define PG8_WAIT_L(n) asm volatile("s_waitcnt lgkmcnt(" #n ")" ::: "memory")
; #define PG8_BAR __builtin_amdgcn_s_barrier()
; #define PG8_SCHED __builtin_amdgcn_sched_barrier(0)
; template <class Epi>
; __device__ __forceinline__ void gemm_phase(LAS unsigned char* lds, const Gemm g, const StaticOrder& S, const Epi& E) {
;     ...
;             PG8_LDA(At, 1, 1); PG8_STAGE(PG8_SA(1, 0), a3, voffA);
;             PG8_BAR; PG8_WAIT_L(0); PG8_MMA(1, 0, At, B0); PG8_BAR; PG8_SCHED;
;             PG8_STAGE(PG8_SB(1, 1), b3 + hstep, voffB);
;             PG8_WAIT_V(6); PG8_BAR; PG8_MMA(1, 1, At, B1); PG8_BAR;
;     __device__ __forceinline__ void operator()(const Acc& acc, const Unit& u, int wr, int wc, int fr, int fq) const {
;         const int pn = u.pn; const int row0 = u.pm * 256 + wr * 64 + fr;
;         bf16_t* base; int ld, cb; bool act;
;         if (vt) { base = vt; ld = TH; cb = 256 * pn; act = false; }
;         else if (gmode) { base = g; ld = 4096; cb = 256 * pn; act = true; }
;         else if (pn < 8) { base = zna; ld = 2048; cb = 256 * pn; act = false; }
;         else if (pn < 16) { base = zqk; ld = 2048; cb = 256 * (pn - 8); act = false; }
;         else if (pn < 24) { base = vo; ld = 2048; cb = 256 * (pn - 16); act = pn >= 20; }
;         else { base = g; ld = 4096; cb = 256 * (pn - 24); act = true; }
	ds_read_b128 v[158:161], v145 offset:49152
	ds_read_b128 v[162:165], v145 offset:50176
	ds_read_b128 v[166:169], v145 offset:51200
	ds_read_b128 v[170:173], v145 offset:52224
	ds_read_b128 v[174:177], v145 offset:53248
	ds_read_b128 v[178:181], v145 offset:54272
	ds_read_b128 v[204:207], v145 offset:55296
	ds_read_b128 v[208:211], v145 offset:56320
	global_load_lds_dwordx4 v128, s[100:101]
	s_mov_b32 m0, s44
	s_nop 0
	global_load_lds_dwordx4 v130, s[100:101]
	s_barrier
	s_waitcnt lgkmcnt(0)
	v_mfma_f32_16x16x32_bf16 v[60:63], v[138:141], v[158:161], v[60:63]
	v_mfma_f32_16x16x32_bf16 v[60:63], v[146:149], v[162:165], v[60:63]
	v_mfma_f32_16x16x32_bf16 v[44:47], v[138:141], v[166:169], v[44:47]
	v_mfma_f32_16x16x32_bf16 v[44:47], v[146:149], v[170:173], v[44:47]
	v_mfma_f32_16x16x32_bf16 v[28:31], v[138:141], v[174:177], v[28:31]
	v_mfma_f32_16x16x32_bf16 v[28:31], v[146:149], v[178:181], v[28:31]
	v_mfma_f32_16x16x32_bf16 v[12:15], v[138:141], v[204:207], v[12:15]
	v_mfma_f32_16x16x32_bf16 v[12:15], v[146:149], v[208:211], v[12:15]
	v_mfma_f32_16x16x32_bf16 v[8:11], v[150:153], v[204:207], v[8:11]
	v_mfma_f32_16x16x32_bf16 v[8:11], v[154:157], v[208:211], v[8:11]
	v_mfma_f32_16x16x32_bf16 v[24:27], v[150:153], v[174:177], v[24:27]
	v_mfma_f32_16x16x32_bf16 v[24:27], v[154:157], v[178:181], v[24:27]
	v_mfma_f32_16x16x32_bf16 v[40:43], v[150:153], v[166:169], v[40:43]
	v_mfma_f32_16x16x32_bf16 v[40:43], v[154:157], v[170:173], v[40:43]
	v_mfma_f32_16x16x32_bf16 v[56:59], v[150:153], v[158:161], v[56:59]
	v_mfma_f32_16x16x32_bf16 v[56:59], v[154:157], v[162:165], v[56:59]
	s_barrier
	s_add_u32 s28, s28, 0x80080
	s_addc_u32 s29, s29, 0
	s_add_i32 s30, s30, s38
	s_mov_b32 m0, s30
	s_nop 0
	global_load_lds_dwordx4 v184, s[28:29]
	s_add_i32 m0, s30, 0x2000
	s_nop 0
	global_load_lds_dwordx4 v132, s[28:29]
	s_waitcnt vmcnt(6)
	s_barrier
	v_mfma_f32_16x16x32_bf16 v[52:55], v[212:215], v[158:161], v[52:55]
	v_mfma_f32_16x16x32_bf16 v[52:55], v[216:219], v[162:165], v[52:55]
	v_mfma_f32_16x16x32_bf16 v[36:39], v[212:215], v[166:169], v[36:39]
	v_mfma_f32_16x16x32_bf16 v[36:39], v[216:219], v[170:173], v[36:39]
	v_mfma_f32_16x16x32_bf16 v[20:23], v[212:215], v[174:177], v[20:23]
	v_mfma_f32_16x16x32_bf16 v[20:23], v[216:219], v[178:181], v[20:23]
	v_mfma_f32_16x16x32_bf16 v[4:7], v[212:215], v[204:207], v[4:7]
	v_mfma_f32_16x16x32_bf16 v[4:7], v[216:219], v[208:211], v[4:7]
	v_mfma_f32_16x16x32_bf16 v[0:3], v[220:223], v[204:207], v[0:3]
	v_mfma_f32_16x16x32_bf16 v[0:3], v[224:227], v[208:211], v[0:3]
	v_mfma_f32_16x16x32_bf16 v[16:19], v[220:223], v[174:177], v[16:19]
	v_mfma_f32_16x16x32_bf16 v[16:19], v[224:227], v[178:181], v[16:19]
	v_mfma_f32_16x16x32_bf16 v[32:35], v[220:223], v[166:169], v[32:35]
	v_mfma_f32_16x16x32_bf16 v[32:35], v[224:227], v[170:173], v[32:35]
	v_mfma_f32_16x16x32_bf16 v[48:51], v[220:223], v[158:161], v[48:51]
	v_mfma_f32_16x16x32_bf16 v[48:51], v[224:227], v[162:165], v[48:51]
	s_add_i32 s43, s43, 2
	s_add_u32 s26, s26, 0x100
	s_addc_u32 s27, s27, 0
	s_add_u32 s34, s34, 0x100
	s_addc_u32 s35, s35, 0
	s_cmp_gt_u32 s43, 29
	s_barrier
	s_cbranch_scc0 .LBB0_366
	s_andn2_b64 vcc, exec, s[16:17]
	s_lshl_b32 s1, s8, 8
	s_cbranch_vccnz .LBB0_378
	s_cmp_lt_i32 s8, 8
	s_cbranch_scc1 .LBB0_410
	s_cmp_gt_u32 s8, 15
	s_mov_b64 s[34:35], -1
	s_cbranch_scc0 .LBB0_375
	s_mov_b64 s[30:31], -1
	s_cmp_gt_u32 s8, 23
	s_mov_b64 s[28:29], -1
	s_cbranch_scc0 .LBB0_372
	s_add_i32 s3, s1, 0xffffe800
	s_mov_b64 s[28:29], 0

; #define PG8_STAGE(bufoff, gbase, voff) do { _Pragma("unroll") for (int _i = 0; _i < 2; ++_i) \
;         __builtin_amdgcn_global_load_lds((const unsigned*)((const char*)(gbase) + (voff)[_i]), (LAS unsigned*)(lds + (bufoff) + ldsw + _i * 8192), 16, 0, 0); } while (0)
; #define PG8_LDA(dst, b, h) do { _Pragma("unroll") for (int m = 0; m < 4; ++m) _Pragma("unroll") for (int k = 0; k < 2; ++k) dst[m][k] = *(const LAS bf16x8*)(lds + PG8_SA(b, h) + aoff + m * 2048 + k * 1024); } while (0)
; #define PG8_LDB(dst, b, h) do { _Pragma("unroll") for (int n = 0; n < 2; ++n) _Pragma("unroll") for (int k = 0; k < 2; ++k) dst[n][k] = *(const LAS bf16x8*)(lds + PG8_SB(b, h) + boff + n * 2048 + k * 1024); } while (0)
; #define PG8_MMA(ai, bj, At, Bt) do { __builtin_amdgcn_s_setprio(1); _Pragma("unroll") for (int m = 0; m < 4; ++m) _Pragma("unroll") for (int n = 0; n < 2; ++n) _Pragma("unroll") for (int k = 0; k < 2; ++k) \
;         acc[ai][bj][m][n] = __builtin_amdgcn_mfma_f32_16x16x32_bf16(Bt[n][k], At[m][k], acc[ai][bj][m][n], 0, 0, 0); __builtin_amdgcn_s_setprio(0); } while (0)
; #define PG8_WAIT_V(n) asm volatile("s_waitcnt vmcnt(" #n ")" ::: "memory")
; #define PG8_WAIT_L(n) asm volatile("s_waitcnt lgkmcnt(" #n ")" ::: "memory")
; #define PG8_BAR __builtin_amdgcn_s_barrier()
; template <class Epi>
; __device__ __forceinline__ void gemm_phase(LAS unsigned char* lds, const Gemm g, const StaticOrder& S, const Epi& E) {
;     ...
;             const bool last = (t == nt - 2);
;             const char* a1 = cA + (size_t)(t + 1) * kstep;
;             const char* a2 = last ? nA : cA + (size_t)(t + 2) * kstep; const char* b2 = last ? nB : cB + (size_t)(t + 2) * kstep;
;             const char* a3 = a2 + kstep; const char* b3 = b2 + kstep;
;             PG8_LDB(B0, 0, 0); PG8_SCHED; PG8_LDA(At, 0, 0); PG8_STAGE(PG8_SA(1, 1), a1 + hstep, voffA);
;             PG8_WAIT_L(8); PG8_BAR; PG8_WAIT_L(0); PG8_MMA(0, 0, At, B0); PG8_BAR; PG8_SCHED;
;             PG8_LDB(B1, 0, 1); PG8_STAGE(PG8_SB(0, 0), b2, voffB);
;             PG8_BAR; PG8_WAIT_L(0); PG8_MMA(0, 1, At, B1); PG8_BAR;
;             PG8_LDA(At, 0, 1); PG8_STAGE(PG8_SA(0, 0), a2, voffA);
;             PG8_BAR; PG8_WAIT_L(0); PG8_MMA(1, 0, At, B0); PG8_BAR; PG8_SCHED;
;             PG8_STAGE(PG8_SB(0, 1), b2 + hstep, voffB);
;             PG8_WAIT_V(6); PG8_BAR; PG8_MMA(1, 1, At, B1); PG8_BAR;
.LBB0_490:
	s_add_u32 s30, s8, 0xfff80080
	s_addc_u32 s31, s9, -1
	s_add_i32 s52, 0, 0x10000
	v_add_u32_e32 v154, s52, v143
	ds_read_b128 v[138:141], v154
	ds_read_b128 v[146:149], v154 offset:1024
	ds_read_b128 v[150:153], v154 offset:2048
	ds_read_b128 v[154:157], v154 offset:3072
	s_cmp_eq_u32 s51, 28
	s_cselect_b32 s35, s3, s31
	s_cselect_b32 s34, s21, s30
	s_cselect_b32 s31, s19, s50
	s_cselect_b32 s30, s43, s47
	s_add_i32 m0, s27, 0xc000
	ds_read_b128 v[158:161], v145
	ds_read_b128 v[162:165], v145 offset:1024
	ds_read_b128 v[166:169], v145 offset:2048
	ds_read_b128 v[170:173], v145 offset:3072
	ds_read_b128 v[174:177], v145 offset:4096
	ds_read_b128 v[178:181], v145 offset:5120
	ds_read_b128 v[204:207], v145 offset:6144
	ds_read_b128 v[208:211], v145 offset:7168
	global_load_lds_dwordx4 v134, s[8:9]
	s_add_i32 m0, s27, 0xe000
	s_nop 0
	global_load_lds_dwordx4 v136, s[8:9]
	s_waitcnt lgkmcnt(8)
	s_barrier
	s_waitcnt lgkmcnt(0)
	v_mfma_f32_16x16x32_bf16 v[124:127], v[138:141], v[158:161], v[124:127]
	v_mfma_f32_16x16x32_bf16 v[124:127], v[146:149], v[162:165], v[124:127]
	v_mfma_f32_16x16x32_bf16 v[108:111], v[138:141], v[166:169], v[108:111]
	v_mfma_f32_16x16x32_bf16 v[108:111], v[146:149], v[170:173], v[108:111]
	v_mfma_f32_16x16x32_bf16 v[92:95], v[138:141], v[174:177], v[92:95]
	v_mfma_f32_16x16x32_bf16 v[92:95], v[146:149], v[178:181], v[92:95]
	v_mfma_f32_16x16x32_bf16 v[76:79], v[138:141], v[204:207], v[76:79]
	v_mfma_f32_16x16x32_bf16 v[76:79], v[146:149], v[208:211], v[76:79]
	v_mfma_f32_16x16x32_bf16 v[72:75], v[150:153], v[204:207], v[72:75]
	v_mfma_f32_16x16x32_bf16 v[72:75], v[154:157], v[208:211], v[72:75]
	v_mfma_f32_16x16x32_bf16 v[88:91], v[150:153], v[174:177], v[88:91]
	v_mfma_f32_16x16x32_bf16 v[88:91], v[154:157], v[178:181], v[88:91]
	v_mfma_f32_16x16x32_bf16 v[104:107], v[150:153], v[166:169], v[104:107]
	v_mfma_f32_16x16x32_bf16 v[104:107], v[154:157], v[170:173], v[104:107]
	v_mfma_f32_16x16x32_bf16 v[120:123], v[150:153], v[158:161], v[120:123]
	v_mfma_f32_16x16x32_bf16 v[120:123], v[154:157], v[162:165], v[120:123]
	s_barrier
	s_add_i32 s56, 0, 0x14000
	v_add_u32_e32 v182, s56, v143
	s_add_i32 s52, s52, s38
	ds_read_b128 v[212:215], v182
	ds_read_b128 v[216:219], v182 offset:1024
	ds_read_b128 v[220:223], v182 offset:2048
	ds_read_b128 v[224:227], v182 offset:3072
	s_mov_b32 m0, s52
	s_add_u32 s98, s30, s58
	s_addc_u32 s99, s31, s59
	global_load_lds_dwordx4 v184, s[30:31]
	s_add_i32 m0, s52, 0x2000
	s_nop 0
	global_load_lds_dwordx4 v132, s[30:31]
	s_barrier
	s_waitcnt lgkmcnt(0)
	v_mfma_f32_16x16x32_bf16 v[116:119], v[212:215], v[158:161], v[116:119]
	v_mfma_f32_16x16x32_bf16 v[116:119], v[216:219], v[162:165], v[116:119]
	v_mfma_f32_16x16x32_bf16 v[100:103], v[212:215], v[166:169], v[100:103]
	v_mfma_f32_16x16x32_bf16 v[100:103], v[216:219], v[170:173], v[100:103]
	v_mfma_f32_16x16x32_bf16 v[84:87], v[212:215], v[174:177], v[84:87]
	v_mfma_f32_16x16x32_bf16 v[84:87], v[216:219], v[178:181], v[84:87]
	v_mfma_f32_16x16x32_bf16 v[68:71], v[212:215], v[204:207], v[68:71]
	v_mfma_f32_16x16x32_bf16 v[68:71], v[216:219], v[208:211], v[68:71]
	v_mfma_f32_16x16x32_bf16 v[64:67], v[220:223], v[204:207], v[64:67]
	v_mfma_f32_16x16x32_bf16 v[64:67], v[224:227], v[208:211], v[64:67]
	v_mfma_f32_16x16x32_bf16 v[80:83], v[220:223], v[174:177], v[80:83]
	v_mfma_f32_16x16x32_bf16 v[80:83], v[224:227], v[178:181], v[80:83]
	v_mfma_f32_16x16x32_bf16 v[96:99], v[220:223], v[166:169], v[96:99]
	v_mfma_f32_16x16x32_bf16 v[96:99], v[224:227], v[170:173], v[96:99]
	v_mfma_f32_16x16x32_bf16 v[112:115], v[220:223], v[158:161], v[112:115]
	v_mfma_f32_16x16x32_bf16 v[112:115], v[224:227], v[162:165], v[112:115]
	s_mov_b32 m0, s27
	s_barrier
	ds_read_b128 v[158:161], v145 offset:16384
	ds_read_b128 v[162:165], v145 offset:17408
	ds_read_b128 v[166:169], v145 offset:18432
	ds_read_b128 v[170:173], v145 offset:19456
	ds_read_b128 v[174:177], v145 offset:20480
	ds_read_b128 v[178:181], v145 offset:21504
	ds_read_b128 v[204:207], v145 offset:22528
	ds_read_b128 v[208:211], v145 offset:23552
	global_load_lds_dwordx4 v128, s[34:35]
	s_add_u32 s100, s34, s58
	s_addc_u32 s101, s35, s59
	s_mov_b32 m0, s29
	s_nop 0
	global_load_lds_dwordx4 v130, s[34:35]
	s_barrier
	s_waitcnt lgkmcnt(0)
	v_mfma_f32_16x16x32_bf16 v[60:63], v[138:141], v[158:161], v[60:63]
	v_mfma_f32_16x16x32_bf16 v[60:63], v[146:149], v[162:165], v[60:63]
	v_mfma_f32_16x16x32_bf16 v[44:47], v[138:141], v[166:169], v[44:47]
	v_mfma_f32_16x16x32_bf16 v[44:47], v[146:149], v[170:173], v[44:47]
	v_mfma_f32_16x16x32_bf16 v[28:31], v[138:141], v[174:177], v[28:31]
	v_mfma_f32_16x16x32_bf16 v[28:31], v[146:149], v[178:181], v[28:31]
	v_mfma_f32_16x16x32_bf16 v[12:15], v[138:141], v[204:207], v[12:15]
	v_mfma_f32_16x16x32_bf16 v[12:15], v[146:149], v[208:211], v[12:15]
	v_mfma_f32_16x16x32_bf16 v[8:11], v[150:153], v[204:207], v[8:11]
	v_mfma_f32_16x16x32_bf16 v[8:11], v[154:157], v[208:211], v[8:11]
	v_mfma_f32_16x16x32_bf16 v[24:27], v[150:153], v[174:177], v[24:27]
	v_mfma_f32_16x16x32_bf16 v[24:27], v[154:157], v[178:181], v[24:27]
	v_mfma_f32_16x16x32_bf16 v[40:43], v[150:153], v[166:169], v[40:43]
	v_mfma_f32_16x16x32_bf16 v[40:43], v[154:157], v[170:173], v[40:43]
	v_mfma_f32_16x16x32_bf16 v[56:59], v[150:153], v[158:161], v[56:59]
	v_mfma_f32_16x16x32_bf16 v[56:59], v[154:157], v[162:165], v[56:59]
	s_barrier
	s_add_u32 s54, s30, 0x80000
	s_addc_u32 s55, s31, 0
	s_add_i32 s52, s56, s38
	s_mov_b32 m0, s52
	s_nop 0
	global_load_lds_dwordx4 v184, s[54:55]
	s_add_i32 m0, s52, 0x2000
	s_nop 0
	global_load_lds_dwordx4 v132, s[54:55]
	s_waitcnt vmcnt(6)
	s_barrier
; #define PG8_STAGE(bufoff, gbase, voff) do { _Pragma("unroll") for (int _i = 0; _i < 2; ++_i) \
;         __builtin_amdgcn_global_load_lds((const unsigned*)((const char*)(gbase) + (voff)[_i]), (LAS unsigned*)(lds + (bufoff) + ldsw + _i * 8192), 16, 0, 0); } while (0)
; #define PG8_LDA(dst, b, h) do { _Pragma("unroll") for (int m = 0; m < 4; ++m) _Pragma("unroll") for (int k = 0; k < 2; ++k) dst[m][k] = *(const LAS bf16x8*)(lds + PG8_SA(b, h) + aoff + m * 2048 + k * 1024); } while (0)
; #define PG8_LDB(dst, b, h) do { _Pragma("unroll") for (int n = 0; n < 2; ++n) _Pragma("unroll") for (int k = 0; k < 2; ++k) dst[n][k] = *(const LAS bf16x8*)(lds + PG8_SB(b, h) + boff + n * 2048 + k * 1024); } while (0)
; #define PG8_MMA(ai, bj, At, Bt) do { __builtin_amdgcn_s_setprio(1); _Pragma("unroll") for (int m = 0; m < 4; ++m) _Pragma("unroll") for (int n = 0; n < 2; ++n) _Pragma("unroll") for (int k = 0; k < 2; ++k) \
;         acc[ai][bj][m][n] = __builtin_amdgcn_mfma_f32_16x16x32_bf16(Bt[n][k], At[m][k], acc[ai][bj][m][n], 0, 0, 0); __builtin_amdgcn_s_setprio(0); } while (0)
; #define PG8_WAIT_V(n) asm volatile("s_waitcnt vmcnt(" #n ")" ::: "memory")
; #define PG8_WAIT_L(n) asm volatile("s_waitcnt lgkmcnt(" #n ")" ::: "memory")
; #define PG8_BAR __builtin_amdgcn_s_barrier()
; #define PG8_SCHED __builtin_amdgcn_sched_barrier(0)
; template <class Epi>
; __device__ __forceinline__ void gemm_phase(LAS unsigned char* lds, const Gemm g, const StaticOrder& S, const Epi& E) {
;     ...
;             PG8_WAIT_V(6); PG8_BAR; PG8_MMA(1, 1, At, B1); PG8_BAR;
;             PG8_LDB(B0, 1, 0); PG8_SCHED; PG8_LDA(At, 1, 0); PG8_STAGE(PG8_SA(0, 1), a2 + hstep, voffA);
;             PG8_WAIT_L(8); PG8_BAR; PG8_WAIT_L(0); PG8_MMA(0, 0, At, B0); PG8_BAR; PG8_SCHED;
;             PG8_LDB(B1, 1, 1); PG8_STAGE(PG8_SB(1, 0), b3, voffB);
;             PG8_BAR; PG8_WAIT_L(0); PG8_MMA(0, 1, At, B1); PG8_BAR;
	v_mfma_f32_16x16x32_bf16 v[52:55], v[212:215], v[158:161], v[52:55]
	v_mfma_f32_16x16x32_bf16 v[52:55], v[216:219], v[162:165], v[52:55]
	v_mfma_f32_16x16x32_bf16 v[36:39], v[212:215], v[166:169], v[36:39]
	v_mfma_f32_16x16x32_bf16 v[36:39], v[216:219], v[170:173], v[36:39]
	v_mfma_f32_16x16x32_bf16 v[20:23], v[212:215], v[174:177], v[20:23]
	v_mfma_f32_16x16x32_bf16 v[20:23], v[216:219], v[178:181], v[20:23]
	v_mfma_f32_16x16x32_bf16 v[4:7], v[212:215], v[204:207], v[4:7]
	v_mfma_f32_16x16x32_bf16 v[4:7], v[216:219], v[208:211], v[4:7]
	v_mfma_f32_16x16x32_bf16 v[0:3], v[220:223], v[204:207], v[0:3]
	v_mfma_f32_16x16x32_bf16 v[0:3], v[224:227], v[208:211], v[0:3]
	v_mfma_f32_16x16x32_bf16 v[16:19], v[220:223], v[174:177], v[16:19]
	v_mfma_f32_16x16x32_bf16 v[16:19], v[224:227], v[178:181], v[16:19]
	v_mfma_f32_16x16x32_bf16 v[32:35], v[220:223], v[166:169], v[32:35]
	v_mfma_f32_16x16x32_bf16 v[32:35], v[224:227], v[170:173], v[32:35]
	v_mfma_f32_16x16x32_bf16 v[48:51], v[220:223], v[158:161], v[48:51]
	v_mfma_f32_16x16x32_bf16 v[48:51], v[224:227], v[162:165], v[48:51]
	s_add_i32 s52, 0, 0x18000
	v_add_u32_e32 v154, s52, v143
	s_barrier
	ds_read_b128 v[138:141], v154
	ds_read_b128 v[146:149], v154 offset:1024
	ds_read_b128 v[150:153], v154 offset:2048
	ds_read_b128 v[154:157], v154 offset:3072
	s_add_u32 s34, s34, 0x80000
	s_addc_u32 s35, s35, 0
	s_mov_b32 m0, s39
	ds_read_b128 v[158:161], v145 offset:32768
	ds_read_b128 v[162:165], v145 offset:33792
	ds_read_b128 v[166:169], v145 offset:34816
	ds_read_b128 v[170:173], v145 offset:35840
	ds_read_b128 v[174:177], v145 offset:36864
	ds_read_b128 v[178:181], v145 offset:37888
	ds_read_b128 v[204:207], v145 offset:38912
	ds_read_b128 v[208:211], v145 offset:39936
	global_load_lds_dwordx4 v128, s[34:35]
	s_mov_b32 m0, s40
	s_nop 0
	global_load_lds_dwordx4 v130, s[34:35]
	s_waitcnt lgkmcnt(8)
	s_barrier
	s_waitcnt lgkmcnt(0)
	v_mfma_f32_16x16x32_bf16 v[124:127], v[138:141], v[158:161], v[124:127]
	v_mfma_f32_16x16x32_bf16 v[124:127], v[146:149], v[162:165], v[124:127]
	v_mfma_f32_16x16x32_bf16 v[108:111], v[138:141], v[166:169], v[108:111]
	v_mfma_f32_16x16x32_bf16 v[108:111], v[146:149], v[170:173], v[108:111]
	v_mfma_f32_16x16x32_bf16 v[92:95], v[138:141], v[174:177], v[92:95]
	v_mfma_f32_16x16x32_bf16 v[92:95], v[146:149], v[178:181], v[92:95]
	v_mfma_f32_16x16x32_bf16 v[76:79], v[138:141], v[204:207], v[76:79]
	v_mfma_f32_16x16x32_bf16 v[76:79], v[146:149], v[208:211], v[76:79]
	v_mfma_f32_16x16x32_bf16 v[72:75], v[150:153], v[204:207], v[72:75]
	v_mfma_f32_16x16x32_bf16 v[72:75], v[154:157], v[208:211], v[72:75]
	v_mfma_f32_16x16x32_bf16 v[88:91], v[150:153], v[174:177], v[88:91]
	v_mfma_f32_16x16x32_bf16 v[88:91], v[154:157], v[178:181], v[88:91]
	v_mfma_f32_16x16x32_bf16 v[104:107], v[150:153], v[166:169], v[104:107]
	v_mfma_f32_16x16x32_bf16 v[104:107], v[154:157], v[170:173], v[104:107]
	v_mfma_f32_16x16x32_bf16 v[120:123], v[150:153], v[158:161], v[120:123]
	v_mfma_f32_16x16x32_bf16 v[120:123], v[154:157], v[162:165], v[120:123]
	s_barrier
	s_add_i32 s34, 0, 0x1c000
	s_add_i32 s35, s52, s38
	v_add_u32_e32 v187, s34, v143
	s_mov_b32 m0, s35
	ds_read_b128 v[212:215], v187
	ds_read_b128 v[216:219], v187 offset:1024
	ds_read_b128 v[220:223], v187 offset:2048
	ds_read_b128 v[224:227], v187 offset:3072
	global_load_lds_dwordx4 v184, s[98:99]
	s_add_i32 m0, s35, 0x2000
	s_nop 0
	global_load_lds_dwordx4 v132, s[98:99]
	s_barrier
	s_waitcnt lgkmcnt(0)
	v_mfma_f32_16x16x32_bf16 v[116:119], v[212:215], v[158:161], v[116:119]
	v_mfma_f32_16x16x32_bf16 v[116:119], v[216:219], v[162:165], v[116:119]
	v_mfma_f32_16x16x32_bf16 v[100:103], v[212:215], v[166:169], v[100:103]
	v_mfma_f32_16x16x32_bf16 v[100:103], v[216:219], v[170:173], v[100:103]
	v_mfma_f32_16x16x32_bf16 v[84:87], v[212:215], v[174:177], v[84:87]
	v_mfma_f32_16x16x32_bf16 v[84:87], v[216:219], v[178:181], v[84:87]
	v_mfma_f32_16x16x32_bf16 v[68:71], v[212:215], v[204:207], v[68:71]
	v_mfma_f32_16x16x32_bf16 v[68:71], v[216:219], v[208:211], v[68:71]
	v_mfma_f32_16x16x32_bf16 v[64:67], v[220:223], v[204:207], v[64:67]
	v_mfma_f32_16x16x32_bf16 v[64:67], v[224:227], v[208:211], v[64:67]
	v_mfma_f32_16x16x32_bf16 v[80:83], v[220:223], v[174:177], v[80:83]
	v_mfma_f32_16x16x32_bf16 v[80:83], v[224:227], v[178:181], v[80:83]
	v_mfma_f32_16x16x32_bf16 v[96:99], v[220:223], v[166:169], v[96:99]
	v_mfma_f32_16x16x32_bf16 v[96:99], v[224:227], v[170:173], v[96:99]
	v_mfma_f32_16x16x32_bf16 v[112:115], v[220:223], v[158:161], v[112:115]
	v_mfma_f32_16x16x32_bf16 v[112:115], v[224:227], v[162:165], v[112:115]
	s_mov_b32 m0, s41
	s_barrier
; __device__ __forceinline__ float sigmoidf_(float x) { return __builtin_amdgcn_rcpf(1.0f + __builtin_amdgcn_exp2f(-1.4426950408889634f * x)); }
; #define PG8_STAGE(bufoff, gbase, voff) do { _Pragma("unroll") for (int _i = 0; _i < 2; ++_i) \
;         __builtin_amdgcn_global_load_lds((const unsigned*)((const char*)(gbase) + (voff)[_i]), (LAS unsigned*)(lds + (bufoff) + ldsw + _i * 8192), 16, 0, 0); } while (0)
; #define PG8_LDA(dst, b, h) do { _Pragma("unroll") for (int m = 0; m < 4; ++m) _Pragma("unroll") for (int k = 0; k < 2; ++k) dst[m][k] = *(const LAS bf16x8*)(lds + PG8_SA(b, h) + aoff + m * 2048 + k * 1024); } while (0)
; #define PG8_MMA(ai, bj, At, Bt) do { __builtin_amdgcn_s_setprio(1); _Pragma("unroll") for (int m = 0; m < 4; ++m) _Pragma("unroll") for (int n = 0; n < 2; ++n) _Pragma("unroll") for (int k = 0; k < 2; ++k) \
;         acc[ai][bj][m][n] = __builtin_amdgcn_mfma_f32_16x16x32_bf16(Bt[n][k], At[m][k], acc[ai][bj][m][n], 0, 0, 0); __builtin_amdgcn_s_setprio(0); } while (0)
; #define PG8_WAIT_V(n) asm volatile("s_waitcnt vmcnt(" #n ")" ::: "memory")
; #define PG8_WAIT_L(n) asm volatile("s_waitcnt lgkmcnt(" #n ")" ::: "memory")
; #define PG8_BAR __builtin_amdgcn_s_barrier()
; #define PG8_SCHED __builtin_amdgcn_sched_barrier(0)
; template <class Epi>
; __device__ __forceinline__ void gemm_phase(LAS unsigned char* lds, const Gemm g, const StaticOrder& S, const Epi& E) {
;     ...
;             PG8_LDA(At, 1, 1); PG8_STAGE(PG8_SA(1, 0), a3, voffA);
;             PG8_BAR; PG8_WAIT_L(0); PG8_MMA(1, 0, At, B0); PG8_BAR; PG8_SCHED;
;             PG8_STAGE(PG8_SB(1, 1), b3 + hstep, voffB);
;             PG8_WAIT_V(6); PG8_BAR; PG8_MMA(1, 1, At, B1); PG8_BAR;
;     __device__ __forceinline__ void operator()(const Acc& acc, const Unit& u, int wr, int wc, int fr, int fq) const {
;     ...
;                 for (int bj = 0; bj < 2; ++bj) { f32x4 v0 = acc[ai][bj][m][0], v1 = acc[ai][bj][m][1];
;                     if (act) {
; #pragma unroll
;                         for (int j = 0; j < 4; ++j) { v0[j] = sigmoidf_(v0[j]); v1[j] = sigmoidf_(v1[j]); } }
	ds_read_b128 v[158:161], v145 offset:49152
	ds_read_b128 v[162:165], v145 offset:50176
	ds_read_b128 v[166:169], v145 offset:51200
	ds_read_b128 v[170:173], v145 offset:52224
	ds_read_b128 v[174:177], v145 offset:53248
	ds_read_b128 v[178:181], v145 offset:54272
	ds_read_b128 v[204:207], v145 offset:55296
	ds_read_b128 v[208:211], v145 offset:56320
	global_load_lds_dwordx4 v128, s[100:101]
	s_mov_b32 m0, s42
	s_nop 0
	global_load_lds_dwordx4 v130, s[100:101]
	s_barrier
	s_waitcnt lgkmcnt(0)
	v_mfma_f32_16x16x32_bf16 v[60:63], v[138:141], v[158:161], v[60:63]
	v_mfma_f32_16x16x32_bf16 v[60:63], v[146:149], v[162:165], v[60:63]
	v_mfma_f32_16x16x32_bf16 v[44:47], v[138:141], v[166:169], v[44:47]
	v_mfma_f32_16x16x32_bf16 v[44:47], v[146:149], v[170:173], v[44:47]
	v_mfma_f32_16x16x32_bf16 v[28:31], v[138:141], v[174:177], v[28:31]
	v_mfma_f32_16x16x32_bf16 v[28:31], v[146:149], v[178:181], v[28:31]
	v_mfma_f32_16x16x32_bf16 v[12:15], v[138:141], v[204:207], v[12:15]
	v_mfma_f32_16x16x32_bf16 v[12:15], v[146:149], v[208:211], v[12:15]
	v_mfma_f32_16x16x32_bf16 v[8:11], v[150:153], v[204:207], v[8:11]
	v_mfma_f32_16x16x32_bf16 v[8:11], v[154:157], v[208:211], v[8:11]
	v_mfma_f32_16x16x32_bf16 v[24:27], v[150:153], v[174:177], v[24:27]
	v_mfma_f32_16x16x32_bf16 v[24:27], v[154:157], v[178:181], v[24:27]
	v_mfma_f32_16x16x32_bf16 v[40:43], v[150:153], v[166:169], v[40:43]
	v_mfma_f32_16x16x32_bf16 v[40:43], v[154:157], v[170:173], v[40:43]
	v_mfma_f32_16x16x32_bf16 v[56:59], v[150:153], v[158:161], v[56:59]
	v_mfma_f32_16x16x32_bf16 v[56:59], v[154:157], v[162:165], v[56:59]
	s_barrier
	s_add_u32 s30, s30, 0x80080
	s_addc_u32 s31, s31, 0
	s_add_i32 s34, s34, s38
	s_mov_b32 m0, s34
	s_nop 0
	global_load_lds_dwordx4 v184, s[30:31]
	s_add_i32 m0, s34, 0x2000
	s_nop 0
	global_load_lds_dwordx4 v132, s[30:31]
	s_waitcnt vmcnt(6)
	s_barrier
	v_mfma_f32_16x16x32_bf16 v[52:55], v[212:215], v[158:161], v[52:55]
	v_mfma_f32_16x16x32_bf16 v[52:55], v[216:219], v[162:165], v[52:55]
	v_mfma_f32_16x16x32_bf16 v[36:39], v[212:215], v[166:169], v[36:39]
	v_mfma_f32_16x16x32_bf16 v[36:39], v[216:219], v[170:173], v[36:39]
	v_mfma_f32_16x16x32_bf16 v[20:23], v[212:215], v[174:177], v[20:23]
	v_mfma_f32_16x16x32_bf16 v[20:23], v[216:219], v[178:181], v[20:23]
	v_mfma_f32_16x16x32_bf16 v[4:7], v[212:215], v[204:207], v[4:7]
	v_mfma_f32_16x16x32_bf16 v[4:7], v[216:219], v[208:211], v[4:7]
	v_mfma_f32_16x16x32_bf16 v[0:3], v[220:223], v[204:207], v[0:3]
	v_mfma_f32_16x16x32_bf16 v[0:3], v[224:227], v[208:211], v[0:3]
	v_mfma_f32_16x16x32_bf16 v[16:19], v[220:223], v[174:177], v[16:19]
	v_mfma_f32_16x16x32_bf16 v[16:19], v[224:227], v[178:181], v[16:19]
	v_mfma_f32_16x16x32_bf16 v[32:35], v[220:223], v[166:169], v[32:35]
	v_mfma_f32_16x16x32_bf16 v[32:35], v[224:227], v[170:173], v[32:35]
	v_mfma_f32_16x16x32_bf16 v[48:51], v[220:223], v[158:161], v[48:51]
	v_mfma_f32_16x16x32_bf16 v[48:51], v[224:227], v[162:165], v[48:51]
	s_add_i32 s51, s51, 2
	s_add_u32 s8, s8, 0x100
	s_addc_u32 s9, s9, 0
	s_add_u32 s47, s47, 0x100
	s_addc_u32 s50, s50, 0
	s_cmp_gt_u32 s51, 29
	s_barrier
	s_cbranch_scc0 .LBB0_490
	v_cndmask_b32_e64 v138, 0, 1, s[16:17]
	v_cmp_ne_u32_e64 s[8:9], 1, v138
	s_andn2_b64 vcc, exec, s[16:17]
	s_cbranch_vccnz .LBB0_493
	v_mul_f32_e32 v124, 0xbfb8aa3b, v124
	v_mul_f32_e32 v120, 0xbfb8aa3b, v120
	v_mul_f32_e32 v125, 0xbfb8aa3b, v125
	v_mul_f32_e32 v121, 0xbfb8aa3b, v121
	v_mul_f32_e32 v126, 0xbfb8aa3b, v126
	v_mul_f32_e32 v122, 0xbfb8aa3b, v122
	v_mul_f32_e32 v127, 0xbfb8aa3b, v127
	v_mul_f32_e32 v123, 0xbfb8aa3b, v123
	v_exp_f32_e32 v124, v124
	v_exp_f32_e32 v120, v120
	v_exp_f32_e32 v125, v125
	v_exp_f32_e32 v121, v121
	v_exp_f32_e32 v126, v126
	v_exp_f32_e32 v122, v122
	v_exp_f32_e32 v127, v127
	v_exp_f32_e32 v123, v123
	v_add_f32_e32 v124, 1.0, v124
	v_add_f32_e32 v120, 1.0, v120
	v_add_f32_e32 v125, 1.0, v125
	v_add_f32_e32 v121, 1.0, v121
	v_add_f32_e32 v126, 1.0, v126
	v_add_f32_e32 v122, 1.0, v122
	v_add_f32_e32 v127, 1.0, v127
	v_add_f32_e32 v123, 1.0, v123
	v_rcp_f32_e32 v124, v124
	v_rcp_f32_e32 v120, v120
	v_rcp_f32_e32 v125, v125
	v_rcp_f32_e32 v121, v121
	v_rcp_f32_e32 v126, v126
	v_rcp_f32_e32 v122, v122
	v_rcp_f32_e32 v127, v127
	v_rcp_f32_e32 v123, v123

; #define PG8_STAGE(bufoff, gbase, voff) do { _Pragma("unroll") for (int _i = 0; _i < 2; ++_i) \
;         __builtin_amdgcn_global_load_lds((const unsigned*)((const char*)(gbase) + (voff)[_i]), (LAS unsigned*)(lds + (bufoff) + ldsw + _i * 8192), 16, 0, 0); } while (0)
; #define PG8_LDA(dst, b, h) do { _Pragma("unroll") for (int m = 0; m < 4; ++m) _Pragma("unroll") for (int k = 0; k < 2; ++k) dst[m][k] = *(const LAS bf16x8*)(lds + PG8_SA(b, h) + aoff + m * 2048 + k * 1024); } while (0)
; #define PG8_LDB(dst, b, h) do { _Pragma("unroll") for (int n = 0; n < 2; ++n) _Pragma("unroll") for (int k = 0; k < 2; ++k) dst[n][k] = *(const LAS bf16x8*)(lds + PG8_SB(b, h) + boff + n * 2048 + k * 1024); } while (0)
; #define PG8_MMA(ai, bj, At, Bt) do { __builtin_amdgcn_s_setprio(1); _Pragma("unroll") for (int m = 0; m < 4; ++m) _Pragma("unroll") for (int n = 0; n < 2; ++n) _Pragma("unroll") for (int k = 0; k < 2; ++k) \
;         acc[ai][bj][m][n] = __builtin_amdgcn_mfma_f32_16x16x32_bf16(Bt[n][k], At[m][k], acc[ai][bj][m][n], 0, 0, 0); __builtin_amdgcn_s_setprio(0); } while (0)
; #define PG8_WAIT_V(n) asm volatile("s_waitcnt vmcnt(" #n ")" ::: "memory")
; #define PG8_WAIT_L(n) asm volatile("s_waitcnt lgkmcnt(" #n ")" ::: "memory")
; #define PG8_BAR __builtin_amdgcn_s_barrier()
; template <class Epi>
; __device__ __forceinline__ void gemm_phase(LAS unsigned char* lds, const Gemm g, const StaticOrder& S, const Epi& E) {
;     ...
;             const bool last = (t == nt - 2);
;             const char* a1 = cA + (size_t)(t + 1) * kstep;
;             const char* a2 = last ? nA : cA + (size_t)(t + 2) * kstep; const char* b2 = last ? nB : cB + (size_t)(t + 2) * kstep;
;             const char* a3 = a2 + kstep; const char* b3 = b2 + kstep;
;             PG8_LDB(B0, 0, 0); PG8_SCHED; PG8_LDA(At, 0, 0); PG8_STAGE(PG8_SA(1, 1), a1 + hstep, voffA);
;             PG8_WAIT_L(8); PG8_BAR; PG8_WAIT_L(0); PG8_MMA(0, 0, At, B0); PG8_BAR; PG8_SCHED;
;             PG8_LDB(B1, 0, 1); PG8_STAGE(PG8_SB(0, 0), b2, voffB);
;             PG8_BAR; PG8_WAIT_L(0); PG8_MMA(0, 1, At, B1); PG8_BAR;
;             PG8_LDA(At, 0, 1); PG8_STAGE(PG8_SA(0, 0), a2, voffA);
;             PG8_BAR; PG8_WAIT_L(0); PG8_MMA(1, 0, At, B0); PG8_BAR; PG8_SCHED;
;             PG8_STAGE(PG8_SB(0, 1), b2 + hstep, voffB);
;             PG8_WAIT_V(6); PG8_BAR; PG8_MMA(1, 1, At, B1); PG8_BAR;
.LBB0_591:
	s_add_i32 s68, s8, 2
	s_add_u32 s36, s0, 0x80
	s_addc_u32 s9, s1, 0
	s_add_i32 s66, 0, 0x10000
	ds_read_b128 v[48:51], v233
	ds_read_b128 v[52:55], v233 offset:1024
	ds_read_b128 v[56:59], v233 offset:2048
	ds_read_b128 v[60:63], v233 offset:3072
	s_cmp_eq_u32 s55, s8
	s_cselect_b32 s8, s34, s36
	s_cselect_b32 s9, s35, s9
	s_cselect_b32 s37, s11, s63
	s_cselect_b32 s36, s10, s43
	v_lshl_add_u64 v[176:177], s[0:1], 0, v[214:215]
	s_add_i32 m0, s44, 0xc000
	ds_read_b128 v[68:71], v248
	ds_read_b128 v[76:79], v248 offset:1024
	ds_read_b128 v[80:83], v248 offset:2048
	ds_read_b128 v[84:87], v248 offset:3072
	ds_read_b128 v[160:163], v248 offset:4096
	ds_read_b128 v[164:167], v248 offset:5120
	ds_read_b128 v[168:171], v248 offset:6144
	ds_read_b128 v[172:175], v248 offset:7168
	global_load_lds_dwordx4 v[176:177], off
	v_lshl_add_u64 v[176:177], s[0:1], 0, v[216:217]
	s_add_i32 m0, s44, 0xe000
	s_nop 0
	global_load_lds_dwordx4 v[176:177], off
	s_waitcnt lgkmcnt(8)
	s_barrier
	s_waitcnt lgkmcnt(0)
	v_mfma_f32_16x16x32_bf16 v[156:159], v[48:51], v[68:71], v[156:159]
	v_mfma_f32_16x16x32_bf16 v[156:159], v[52:55], v[76:79], v[156:159]
	v_mfma_f32_16x16x32_bf16 v[140:143], v[48:51], v[80:83], v[140:143]
	v_mfma_f32_16x16x32_bf16 v[140:143], v[52:55], v[84:87], v[140:143]
	v_mfma_f32_16x16x32_bf16 v[124:127], v[48:51], v[160:163], v[124:127]
	v_mfma_f32_16x16x32_bf16 v[124:127], v[52:55], v[164:167], v[124:127]
	v_mfma_f32_16x16x32_bf16 v[108:111], v[48:51], v[168:171], v[108:111]
	v_mfma_f32_16x16x32_bf16 v[108:111], v[52:55], v[172:175], v[108:111]
	v_mfma_f32_16x16x32_bf16 v[104:107], v[56:59], v[168:171], v[104:107]
	v_mfma_f32_16x16x32_bf16 v[104:107], v[60:63], v[172:175], v[104:107]
	v_mfma_f32_16x16x32_bf16 v[120:123], v[56:59], v[160:163], v[120:123]
	v_mfma_f32_16x16x32_bf16 v[120:123], v[60:63], v[164:167], v[120:123]
	v_mfma_f32_16x16x32_bf16 v[136:139], v[56:59], v[80:83], v[136:139]
	v_mfma_f32_16x16x32_bf16 v[136:139], v[60:63], v[84:87], v[136:139]
	v_mfma_f32_16x16x32_bf16 v[152:155], v[56:59], v[68:71], v[152:155]
	v_mfma_f32_16x16x32_bf16 v[152:155], v[60:63], v[76:79], v[152:155]
	s_barrier
	s_add_i32 s67, 0, 0x14000
	s_add_i32 s66, s66, s41
	s_mov_b32 m0, s66
	ds_read_b128 v[176:179], v233 offset:16384
	ds_read_b128 v[180:183], v233 offset:17408
	ds_read_b128 v[218:221], v233 offset:18432
	ds_read_b128 v[222:225], v233 offset:19456
	global_load_lds_dwordx4 v184, s[36:37]
	s_add_u32 s98, s36, s58
	s_addc_u32 s99, s37, s59
	s_add_i32 m0, s66, 0x2000
	s_nop 0
	global_load_lds_dwordx4 v212, s[36:37]
	s_barrier
	s_waitcnt lgkmcnt(0)
	v_mfma_f32_16x16x32_bf16 v[148:151], v[176:179], v[68:71], v[148:151]
	v_mfma_f32_16x16x32_bf16 v[68:71], v[218:221], v[68:71], v[144:147]
	v_mfma_f32_16x16x32_bf16 v[148:151], v[180:183], v[76:79], v[148:151]
	v_mfma_f32_16x16x32_bf16 v[68:71], v[222:225], v[76:79], v[68:71]
	v_mfma_f32_16x16x32_bf16 v[76:79], v[176:179], v[80:83], v[132:135]
	v_mfma_f32_16x16x32_bf16 v[80:83], v[218:221], v[80:83], v[128:131]
	v_mfma_f32_16x16x32_bf16 v[112:115], v[218:221], v[160:163], v[112:115]
	v_mfma_f32_16x16x32_bf16 v[100:103], v[176:179], v[168:171], v[100:103]
	v_mfma_f32_16x16x32_bf16 v[96:99], v[218:221], v[168:171], v[96:99]
	v_mfma_f32_16x16x32_bf16 v[76:79], v[180:183], v[84:87], v[76:79]
	v_mfma_f32_16x16x32_bf16 v[80:83], v[222:225], v[84:87], v[80:83]
	v_mfma_f32_16x16x32_bf16 v[84:87], v[176:179], v[160:163], v[116:119]
	v_mfma_f32_16x16x32_bf16 v[112:115], v[222:225], v[164:167], v[112:115]
	v_mfma_f32_16x16x32_bf16 v[100:103], v[180:183], v[172:175], v[100:103]
	v_mfma_f32_16x16x32_bf16 v[96:99], v[222:225], v[172:175], v[96:99]
	v_mfma_f32_16x16x32_bf16 v[84:87], v[180:183], v[164:167], v[84:87]
	s_mov_b32 m0, s44
	s_barrier
	ds_read_b128 v[116:119], v248 offset:16384
	ds_read_b128 v[128:131], v248 offset:17408
	ds_read_b128 v[132:135], v248 offset:18432
	ds_read_b128 v[144:147], v248 offset:19456
	ds_read_b128 v[160:163], v248 offset:20480
	ds_read_b128 v[164:167], v248 offset:21504
	ds_read_b128 v[168:171], v248 offset:22528
	ds_read_b128 v[172:175], v248 offset:23552
	global_load_lds_dwordx4 v208, s[8:9]
	s_add_u32 s100, s8, s58
	s_addc_u32 s101, s9, s59
	s_mov_b32 m0, s45
	s_nop 0
	global_load_lds_dwordx4 v210, s[8:9]
	s_barrier
	s_waitcnt lgkmcnt(0)
	v_mfma_f32_16x16x32_bf16 v[92:95], v[48:51], v[116:119], v[92:95]
	v_mfma_f32_16x16x32_bf16 v[92:95], v[52:55], v[128:131], v[92:95]
	v_mfma_f32_16x16x32_bf16 v[44:47], v[48:51], v[132:135], v[44:47]
	v_mfma_f32_16x16x32_bf16 v[44:47], v[52:55], v[144:147], v[44:47]
	v_mfma_f32_16x16x32_bf16 v[28:31], v[48:51], v[160:163], v[28:31]
	v_mfma_f32_16x16x32_bf16 v[28:31], v[52:55], v[164:167], v[28:31]
	v_mfma_f32_16x16x32_bf16 v[12:15], v[48:51], v[168:171], v[12:15]
	v_mfma_f32_16x16x32_bf16 v[12:15], v[52:55], v[172:175], v[12:15]
	v_mfma_f32_16x16x32_bf16 v[8:11], v[56:59], v[168:171], v[8:11]
	v_mfma_f32_16x16x32_bf16 v[8:11], v[60:63], v[172:175], v[8:11]
	v_mfma_f32_16x16x32_bf16 v[24:27], v[56:59], v[160:163], v[24:27]
	v_mfma_f32_16x16x32_bf16 v[24:27], v[60:63], v[164:167], v[24:27]
	v_mfma_f32_16x16x32_bf16 v[40:43], v[56:59], v[132:135], v[40:43]
	v_mfma_f32_16x16x32_bf16 v[40:43], v[60:63], v[144:147], v[40:43]
	v_mfma_f32_16x16x32_bf16 v[88:91], v[56:59], v[116:119], v[88:91]
	v_mfma_f32_16x16x32_bf16 v[88:91], v[60:63], v[128:131], v[88:91]
	s_barrier
	s_add_u32 s36, s36, s52
	s_addc_u32 s37, s37, 0
	s_add_i32 s66, s67, s41
	v_lshl_add_u64 v[190:191], s[36:37], 0, v[184:185]
	s_mov_b32 m0, s66
	v_lshl_add_u64 v[192:193], s[36:37], 0, v[212:213]
	global_load_lds_dwordx4 v[190:191], off
	s_add_i32 m0, s66, 0x2000
	s_nop 0
	global_load_lds_dwordx4 v[192:193], off
	s_waitcnt vmcnt(6)
	s_barrier
; #define PG8_STAGE(bufoff, gbase, voff) do { _Pragma("unroll") for (int _i = 0; _i < 2; ++_i) \
;         __builtin_amdgcn_global_load_lds((const unsigned*)((const char*)(gbase) + (voff)[_i]), (LAS unsigned*)(lds + (bufoff) + ldsw + _i * 8192), 16, 0, 0); } while (0)
; #define PG8_LDA(dst, b, h) do { _Pragma("unroll") for (int m = 0; m < 4; ++m) _Pragma("unroll") for (int k = 0; k < 2; ++k) dst[m][k] = *(const LAS bf16x8*)(lds + PG8_SA(b, h) + aoff + m * 2048 + k * 1024); } while (0)
; #define PG8_LDB(dst, b, h) do { _Pragma("unroll") for (int n = 0; n < 2; ++n) _Pragma("unroll") for (int k = 0; k < 2; ++k) dst[n][k] = *(const LAS bf16x8*)(lds + PG8_SB(b, h) + boff + n * 2048 + k * 1024); } while (0)
; #define PG8_MMA(ai, bj, At, Bt) do { __builtin_amdgcn_s_setprio(1); _Pragma("unroll") for (int m = 0; m < 4; ++m) _Pragma("unroll") for (int n = 0; n < 2; ++n) _Pragma("unroll") for (int k = 0; k < 2; ++k) \
;         acc[ai][bj][m][n] = __builtin_amdgcn_mfma_f32_16x16x32_bf16(Bt[n][k], At[m][k], acc[ai][bj][m][n], 0, 0, 0); __builtin_amdgcn_s_setprio(0); } while (0)
; #define PG8_WAIT_V(n) asm volatile("s_waitcnt vmcnt(" #n ")" ::: "memory")
; #define PG8_WAIT_L(n) asm volatile("s_waitcnt lgkmcnt(" #n ")" ::: "memory")
; #define PG8_BAR __builtin_amdgcn_s_barrier()
; #define PG8_SCHED __builtin_amdgcn_sched_barrier(0)
; template <class Epi>
; __device__ __forceinline__ void gemm_phase(LAS unsigned char* lds, const Gemm g, const StaticOrder& S, const Epi& E) {
;     ...
;             PG8_WAIT_V(6); PG8_BAR; PG8_MMA(1, 1, At, B1); PG8_BAR;
;             PG8_LDB(B0, 1, 0); PG8_SCHED; PG8_LDA(At, 1, 0); PG8_STAGE(PG8_SA(0, 1), a2 + hstep, voffA);
;             PG8_WAIT_L(8); PG8_BAR; PG8_WAIT_L(0); PG8_MMA(0, 0, At, B0); PG8_BAR; PG8_SCHED;
;             PG8_LDB(B1, 1, 1); PG8_STAGE(PG8_SB(1, 0), b3, voffB);
;             PG8_BAR; PG8_WAIT_L(0); PG8_MMA(0, 1, At, B1); PG8_BAR;
	v_mfma_f32_16x16x32_bf16 v[36:39], v[176:179], v[132:135], v[36:39]
	v_mfma_f32_16x16x32_bf16 v[36:39], v[180:183], v[144:147], v[36:39]
	v_mfma_f32_16x16x32_bf16 v[20:23], v[176:179], v[160:163], v[20:23]
	v_mfma_f32_16x16x32_bf16 v[20:23], v[180:183], v[164:167], v[20:23]
	v_mfma_f32_16x16x32_bf16 v[4:7], v[176:179], v[168:171], v[4:7]
	v_mfma_f32_16x16x32_bf16 v[4:7], v[180:183], v[172:175], v[4:7]
	v_mfma_f32_16x16x32_bf16 v[48:51], v[176:179], v[116:119], v[72:75]
	v_mfma_f32_16x16x32_bf16 v[48:51], v[180:183], v[128:131], v[48:51]
	v_mfma_f32_16x16x32_bf16 v[52:55], v[218:221], v[116:119], v[64:67]
	v_mfma_f32_16x16x32_bf16 v[52:55], v[222:225], v[128:131], v[52:55]
	v_mfma_f32_16x16x32_bf16 v[0:3], v[218:221], v[168:171], v[0:3]
	v_mfma_f32_16x16x32_bf16 v[0:3], v[222:225], v[172:175], v[0:3]
	v_mfma_f32_16x16x32_bf16 v[16:19], v[218:221], v[160:163], v[16:19]
	v_mfma_f32_16x16x32_bf16 v[16:19], v[222:225], v[164:167], v[16:19]
	v_mfma_f32_16x16x32_bf16 v[32:35], v[218:221], v[132:135], v[32:35]
	v_mfma_f32_16x16x32_bf16 v[32:35], v[222:225], v[144:147], v[32:35]
	s_add_i32 s36, 0, 0x18000
	s_barrier
	ds_read_b128 v[56:59], v233 offset:32768
	ds_read_b128 v[60:63], v233 offset:33792
	ds_read_b128 v[64:67], v233 offset:34816
	ds_read_b128 v[72:75], v233 offset:35840
	s_add_u32 s8, s8, s52
	s_addc_u32 s9, s9, 0
	s_mov_b32 m0, s46
	ds_read_b128 v[116:119], v248 offset:32768
	ds_read_b128 v[128:131], v248 offset:33792
	ds_read_b128 v[160:163], v248 offset:34816
	ds_read_b128 v[164:167], v248 offset:35840
	ds_read_b128 v[168:171], v248 offset:36864
	ds_read_b128 v[172:175], v248 offset:37888
	ds_read_b128 v[176:179], v248 offset:38912
	ds_read_b128 v[180:183], v248 offset:39936
	global_load_lds_dwordx4 v208, s[8:9]
	v_lshl_add_u64 v[132:133], s[8:9], 0, v[210:211]
	s_mov_b32 m0, s47
	s_nop 0
	global_load_lds_dwordx4 v[132:133], off
	s_waitcnt lgkmcnt(8)
	s_barrier
	s_waitcnt lgkmcnt(0)
	v_mfma_f32_16x16x32_bf16 v[132:135], v[56:59], v[116:119], v[156:159]
	v_mfma_f32_16x16x32_bf16 v[156:159], v[60:63], v[128:131], v[132:135]
	v_mfma_f32_16x16x32_bf16 v[132:135], v[64:67], v[116:119], v[152:155]
	v_mfma_f32_16x16x32_bf16 v[152:155], v[72:75], v[128:131], v[132:135]
	v_mfma_f32_16x16x32_bf16 v[132:135], v[56:59], v[160:163], v[140:143]
	v_mfma_f32_16x16x32_bf16 v[140:143], v[60:63], v[164:167], v[132:135]
	v_mfma_f32_16x16x32_bf16 v[132:135], v[64:67], v[160:163], v[136:139]
	v_mfma_f32_16x16x32_bf16 v[124:127], v[56:59], v[168:171], v[124:127]
	v_mfma_f32_16x16x32_bf16 v[120:123], v[64:67], v[168:171], v[120:123]
	v_mfma_f32_16x16x32_bf16 v[108:111], v[56:59], v[176:179], v[108:111]
	v_mfma_f32_16x16x32_bf16 v[104:107], v[64:67], v[176:179], v[104:107]
	v_mfma_f32_16x16x32_bf16 v[136:139], v[72:75], v[164:167], v[132:135]
	v_mfma_f32_16x16x32_bf16 v[124:127], v[60:63], v[172:175], v[124:127]
	v_mfma_f32_16x16x32_bf16 v[120:123], v[72:75], v[172:175], v[120:123]
	v_mfma_f32_16x16x32_bf16 v[108:111], v[60:63], v[180:183], v[108:111]
	v_mfma_f32_16x16x32_bf16 v[104:107], v[72:75], v[180:183], v[104:107]
	s_barrier
	s_add_i32 s8, 0, 0x1c000
	s_add_i32 s9, s36, s41
	ds_read_b128 v[218:221], v233 offset:49152
	ds_read_b128 v[222:225], v233 offset:50176
	ds_read_b128 v[226:229], v233 offset:51200
	ds_read_b128 v[204:207], v233 offset:52224
	s_mov_b32 m0, s9
	s_nop 0
	global_load_lds_dwordx4 v184, s[98:99]
	s_add_i32 m0, s9, 0x2000
	s_nop 0
	global_load_lds_dwordx4 v212, s[98:99]
	s_barrier
	s_waitcnt lgkmcnt(0)
	v_mfma_f32_16x16x32_bf16 v[68:71], v[226:229], v[116:119], v[68:71]
	v_mfma_f32_16x16x32_bf16 v[132:135], v[218:221], v[116:119], v[148:151]
	v_mfma_f32_16x16x32_bf16 v[144:147], v[204:207], v[128:131], v[68:71]
	v_mfma_f32_16x16x32_bf16 v[68:71], v[218:221], v[160:163], v[76:79]
	v_mfma_f32_16x16x32_bf16 v[148:151], v[222:225], v[128:131], v[132:135]
	v_mfma_f32_16x16x32_bf16 v[132:135], v[222:225], v[164:167], v[68:71]
	v_mfma_f32_16x16x32_bf16 v[68:71], v[226:229], v[160:163], v[80:83]
	v_mfma_f32_16x16x32_bf16 v[128:131], v[204:207], v[164:167], v[68:71]
	v_mfma_f32_16x16x32_bf16 v[68:71], v[218:221], v[168:171], v[84:87]
	v_mfma_f32_16x16x32_bf16 v[116:119], v[222:225], v[172:175], v[68:71]
	v_mfma_f32_16x16x32_bf16 v[68:71], v[226:229], v[168:171], v[112:115]
	v_mfma_f32_16x16x32_bf16 v[112:115], v[204:207], v[172:175], v[68:71]
	v_mfma_f32_16x16x32_bf16 v[68:71], v[218:221], v[176:179], v[100:103]
	v_mfma_f32_16x16x32_bf16 v[100:103], v[222:225], v[180:183], v[68:71]
	v_mfma_f32_16x16x32_bf16 v[68:71], v[226:229], v[176:179], v[96:99]
	v_mfma_f32_16x16x32_bf16 v[96:99], v[204:207], v[180:183], v[68:71]
	s_mov_b32 m0, s50
	s_barrier
; #define PG8_STAGE(bufoff, gbase, voff) do { _Pragma("unroll") for (int _i = 0; _i < 2; ++_i) \
;         __builtin_amdgcn_global_load_lds((const unsigned*)((const char*)(gbase) + (voff)[_i]), (LAS unsigned*)(lds + (bufoff) + ldsw + _i * 8192), 16, 0, 0); } while (0)
; #define PG8_LDA(dst, b, h) do { _Pragma("unroll") for (int m = 0; m < 4; ++m) _Pragma("unroll") for (int k = 0; k < 2; ++k) dst[m][k] = *(const LAS bf16x8*)(lds + PG8_SA(b, h) + aoff + m * 2048 + k * 1024); } while (0)
; #define PG8_MMA(ai, bj, At, Bt) do { __builtin_amdgcn_s_setprio(1); _Pragma("unroll") for (int m = 0; m < 4; ++m) _Pragma("unroll") for (int n = 0; n < 2; ++n) _Pragma("unroll") for (int k = 0; k < 2; ++k) \
;         acc[ai][bj][m][n] = __builtin_amdgcn_mfma_f32_16x16x32_bf16(Bt[n][k], At[m][k], acc[ai][bj][m][n], 0, 0, 0); __builtin_amdgcn_s_setprio(0); } while (0)
; #define PG8_WAIT_V(n) asm volatile("s_waitcnt vmcnt(" #n ")" ::: "memory")
; #define PG8_WAIT_L(n) asm volatile("s_waitcnt lgkmcnt(" #n ")" ::: "memory")
; #define PG8_BAR __builtin_amdgcn_s_barrier()
; #define PG8_SCHED __builtin_amdgcn_sched_barrier(0)
; template <class Epi>
; __device__ __forceinline__ void gemm_phase(LAS unsigned char* lds, const Gemm g, const StaticOrder& S, const Epi& E) {
;     ...
;             PG8_LDA(At, 1, 1); PG8_STAGE(PG8_SA(1, 0), a3, voffA);
;             PG8_BAR; PG8_WAIT_L(0); PG8_MMA(1, 0, At, B0); PG8_BAR; PG8_SCHED;
;             PG8_STAGE(PG8_SB(1, 1), b3 + hstep, voffB);
;             PG8_WAIT_V(6); PG8_BAR; PG8_MMA(1, 1, At, B1); PG8_BAR;
;     __device__ __forceinline__ void operator()(const Acc& acc, const Unit& u, int wr, int wc, int fr, int fq) const {
;     ...
;         if (stats) {
; #pragma unroll
;             for (int bj = 0; bj < 2; ++bj)
; #pragma unroll
;                 for (int n = 0; n < 2; ++n) { gv[bj][n] = *(const f32x4*)(lg + col0 + bj * 128 + n * 4); bv[bj][n] = *(const f32x4*)(lb + col0 + bj * 128 + n * 4); } }
	s_nop 2
	ds_read_b128 v[68:71], v248 offset:49152
	ds_read_b128 v[76:79], v248 offset:50176
	ds_read_b128 v[80:83], v248 offset:51200
	ds_read_b128 v[84:87], v248 offset:52224
	ds_read_b128 v[160:163], v248 offset:53248
	ds_read_b128 v[164:167], v248 offset:54272
	ds_read_b128 v[168:171], v248 offset:55296
	ds_read_b128 v[172:175], v248 offset:56320
	global_load_lds_dwordx4 v208, s[100:101]
	s_mov_b32 m0, s51
	s_nop 0
	global_load_lds_dwordx4 v210, s[100:101]
	s_barrier
	s_waitcnt lgkmcnt(0)
	v_mfma_f32_16x16x32_bf16 v[92:95], v[56:59], v[68:71], v[92:95]
	v_mfma_f32_16x16x32_bf16 v[92:95], v[60:63], v[76:79], v[92:95]
	v_mfma_f32_16x16x32_bf16 v[44:47], v[56:59], v[80:83], v[44:47]
	v_mfma_f32_16x16x32_bf16 v[44:47], v[60:63], v[84:87], v[44:47]
	v_mfma_f32_16x16x32_bf16 v[28:31], v[56:59], v[160:163], v[28:31]
	v_mfma_f32_16x16x32_bf16 v[28:31], v[60:63], v[164:167], v[28:31]
	v_mfma_f32_16x16x32_bf16 v[12:15], v[56:59], v[168:171], v[12:15]
	v_mfma_f32_16x16x32_bf16 v[12:15], v[60:63], v[172:175], v[12:15]
	v_mfma_f32_16x16x32_bf16 v[8:11], v[64:67], v[168:171], v[8:11]
	v_mfma_f32_16x16x32_bf16 v[8:11], v[72:75], v[172:175], v[8:11]
	v_mfma_f32_16x16x32_bf16 v[24:27], v[64:67], v[160:163], v[24:27]
	v_mfma_f32_16x16x32_bf16 v[24:27], v[72:75], v[164:167], v[24:27]
	v_mfma_f32_16x16x32_bf16 v[40:43], v[64:67], v[80:83], v[40:43]
	v_mfma_f32_16x16x32_bf16 v[40:43], v[72:75], v[84:87], v[40:43]
	v_mfma_f32_16x16x32_bf16 v[88:91], v[64:67], v[68:71], v[88:91]
	v_mfma_f32_16x16x32_bf16 v[88:91], v[72:75], v[76:79], v[88:91]
	s_barrier
	s_add_i32 s8, s8, s41
	v_lshl_add_u64 v[56:57], v[190:191], 0, s[58:59]
	s_mov_b32 m0, s8
	s_nop 0
	global_load_lds_dwordx4 v[56:57], off
	v_lshl_add_u64 v[56:57], v[192:193], 0, s[58:59]
	s_add_i32 m0, s8, 0x2000
	s_nop 0
	global_load_lds_dwordx4 v[56:57], off
	s_waitcnt vmcnt(6)
	s_barrier
	v_mfma_f32_16x16x32_bf16 v[48:51], v[218:221], v[68:71], v[48:51]
	v_mfma_f32_16x16x32_bf16 v[72:75], v[222:225], v[76:79], v[48:51]
	v_mfma_f32_16x16x32_bf16 v[48:51], v[226:229], v[68:71], v[52:55]
	v_mfma_f32_16x16x32_bf16 v[36:39], v[218:221], v[80:83], v[36:39]
	v_mfma_f32_16x16x32_bf16 v[32:35], v[226:229], v[80:83], v[32:35]
	v_mfma_f32_16x16x32_bf16 v[20:23], v[218:221], v[160:163], v[20:23]
	v_mfma_f32_16x16x32_bf16 v[16:19], v[226:229], v[160:163], v[16:19]
	v_mfma_f32_16x16x32_bf16 v[4:7], v[218:221], v[168:171], v[4:7]
	v_mfma_f32_16x16x32_bf16 v[0:3], v[226:229], v[168:171], v[0:3]
	v_mfma_f32_16x16x32_bf16 v[64:67], v[204:207], v[76:79], v[48:51]
	v_mfma_f32_16x16x32_bf16 v[36:39], v[222:225], v[84:87], v[36:39]
	v_mfma_f32_16x16x32_bf16 v[32:35], v[204:207], v[84:87], v[32:35]
	v_mfma_f32_16x16x32_bf16 v[20:23], v[222:225], v[164:167], v[20:23]
	v_mfma_f32_16x16x32_bf16 v[16:19], v[204:207], v[164:167], v[16:19]
	v_mfma_f32_16x16x32_bf16 v[4:7], v[222:225], v[172:175], v[4:7]
	v_mfma_f32_16x16x32_bf16 v[0:3], v[204:207], v[172:175], v[0:3]
	s_add_u32 s0, s0, 0x100
	s_addc_u32 s1, s1, 0
	s_add_u32 s43, s43, 0x100
	s_addc_u32 s63, s63, 0
	s_cmp_ge_u32 s68, s54
	s_mov_b32 s8, s68
	s_barrier
	s_cbranch_scc0 .LBB0_591
	v_lshl_or_b32 v224, s42, 8, v247
	v_cndmask_b32_e64 v48, 0, 1, s[30:31]
	v_cmp_ne_u32_e64 s[8:9], 1, v48
	s_andn2_b64 vcc, exec, s[30:31]
	v_ashrrev_i32_e32 v225, 31, v224
	s_cbranch_vccnz .LBB0_594
	v_lshlrev_b64 v[48:49], 2, v[224:225]
	v_lshl_add_u64 v[52:53], s[20:21], 0, v[48:49]
	v_lshl_add_u64 v[60:61], s[22:23], 0, v[48:49]
	global_load_dwordx4 v[68:71], v[52:53], off offset:16
	global_load_dwordx4 v[80:83], v[52:53], off
	global_load_dwordx4 v[76:79], v[60:61], off offset:16
	global_load_dwordx4 v[84:87], v[60:61], off
	global_load_dwordx4 v[48:51], v[52:53], off offset:528
	global_load_dwordx4 v[56:59], v[52:53], off offset:512
	s_nop 0
	global_load_dwordx4 v[52:55], v[60:61], off offset:528
	s_nop 0
	global_load_dwordx4 v[60:63], v[60:61], off offset:512

; #define PG8_STAGE(bufoff, gbase, voff) do { _Pragma("unroll") for (int _i = 0; _i < 2; ++_i) \
;         __builtin_amdgcn_global_load_lds((const unsigned*)((const char*)(gbase) + (voff)[_i]), (LAS unsigned*)(lds + (bufoff) + ldsw + _i * 8192), 16, 0, 0); } while (0)
; #define PG8_LDA(dst, b, h) do { _Pragma("unroll") for (int m = 0; m < 4; ++m) _Pragma("unroll") for (int k = 0; k < 2; ++k) dst[m][k] = *(const LAS bf16x8*)(lds + PG8_SA(b, h) + aoff + m * 2048 + k * 1024); } while (0)
; #define PG8_LDB(dst, b, h) do { _Pragma("unroll") for (int n = 0; n < 2; ++n) _Pragma("unroll") for (int k = 0; k < 2; ++k) dst[n][k] = *(const LAS bf16x8*)(lds + PG8_SB(b, h) + boff + n * 2048 + k * 1024); } while (0)
; #define PG8_MMA(ai, bj, At, Bt) do { __builtin_amdgcn_s_setprio(1); _Pragma("unroll") for (int m = 0; m < 4; ++m) _Pragma("unroll") for (int n = 0; n < 2; ++n) _Pragma("unroll") for (int k = 0; k < 2; ++k) \
;         acc[ai][bj][m][n] = __builtin_amdgcn_mfma_f32_16x16x32_bf16(Bt[n][k], At[m][k], acc[ai][bj][m][n], 0, 0, 0); __builtin_amdgcn_s_setprio(0); } while (0)
; #define PG8_WAIT_V(n) asm volatile("s_waitcnt vmcnt(" #n ")" ::: "memory")
; #define PG8_WAIT_L(n) asm volatile("s_waitcnt lgkmcnt(" #n ")" ::: "memory")
; #define PG8_BAR __builtin_amdgcn_s_barrier()
; template <class Epi>
; __device__ __forceinline__ void gemm_phase(LAS unsigned char* lds, const Gemm g, const StaticOrder& S, const Epi& E) {
;     ...
;             const bool last = (t == nt - 2);
;             const char* a1 = cA + (size_t)(t + 1) * kstep;
;             const char* a2 = last ? nA : cA + (size_t)(t + 2) * kstep; const char* b2 = last ? nB : cB + (size_t)(t + 2) * kstep;
;             const char* a3 = a2 + kstep; const char* b3 = b2 + kstep;
;             PG8_LDB(B0, 0, 0); PG8_SCHED; PG8_LDA(At, 0, 0); PG8_STAGE(PG8_SA(1, 1), a1 + hstep, voffA);
;             PG8_WAIT_L(8); PG8_BAR; PG8_WAIT_L(0); PG8_MMA(0, 0, At, B0); PG8_BAR; PG8_SCHED;
;             PG8_LDB(B1, 0, 1); PG8_STAGE(PG8_SB(0, 0), b2, voffB);
;             PG8_BAR; PG8_WAIT_L(0); PG8_MMA(0, 1, At, B1); PG8_BAR;
;             PG8_LDA(At, 0, 1); PG8_STAGE(PG8_SA(0, 0), a2, voffA);
;             PG8_BAR; PG8_WAIT_L(0); PG8_MMA(1, 0, At, B0); PG8_BAR; PG8_SCHED;
;             PG8_STAGE(PG8_SB(0, 1), b2 + hstep, voffB);
;             PG8_WAIT_V(6); PG8_BAR; PG8_MMA(1, 1, At, B1); PG8_BAR;
.LBB0_721:
	s_add_u32 s18, s16, 0xfff80080
	s_addc_u32 s19, s17, -1
	s_add_i32 s39, 0, 0x10000
	ds_read_b128 v[142:145], v139
	ds_read_b128 v[146:149], v139 offset:1024
	ds_read_b128 v[150:153], v139 offset:2048
	ds_read_b128 v[154:157], v139 offset:3072
	s_cmp_eq_u32 s38, 28
	s_cselect_b32 s21, s9, s19
	s_cselect_b32 s20, s34, s18
	s_cselect_b32 s19, s1, s37
	s_cselect_b32 s18, s35, s36
	s_add_i32 m0, s15, 0xc000
	ds_read_b128 v[158:161], v141
	ds_read_b128 v[162:165], v141 offset:1024
	ds_read_b128 v[166:169], v141 offset:2048
	ds_read_b128 v[170:173], v141 offset:3072
	ds_read_b128 v[174:177], v141 offset:4096
	ds_read_b128 v[178:181], v141 offset:5120
	ds_read_b128 v[208:211], v141 offset:6144
	ds_read_b128 v[212:215], v141 offset:7168
	global_load_lds_dwordx4 v134, s[16:17]
	s_add_i32 m0, s15, 0xe000
	s_nop 0
	global_load_lds_dwordx4 v136, s[16:17]
	s_waitcnt lgkmcnt(8)
	s_barrier
	s_waitcnt lgkmcnt(0)
	v_mfma_f32_16x16x32_bf16 v[124:127], v[142:145], v[158:161], v[124:127]
	v_mfma_f32_16x16x32_bf16 v[124:127], v[146:149], v[162:165], v[124:127]
	v_mfma_f32_16x16x32_bf16 v[108:111], v[142:145], v[166:169], v[108:111]
	v_mfma_f32_16x16x32_bf16 v[108:111], v[146:149], v[170:173], v[108:111]
	v_mfma_f32_16x16x32_bf16 v[92:95], v[142:145], v[174:177], v[92:95]
	v_mfma_f32_16x16x32_bf16 v[92:95], v[146:149], v[178:181], v[92:95]
	v_mfma_f32_16x16x32_bf16 v[76:79], v[142:145], v[208:211], v[76:79]
	v_mfma_f32_16x16x32_bf16 v[76:79], v[146:149], v[212:215], v[76:79]
	v_mfma_f32_16x16x32_bf16 v[68:71], v[150:153], v[208:211], v[68:71]
	v_mfma_f32_16x16x32_bf16 v[68:71], v[154:157], v[212:215], v[68:71]
	v_mfma_f32_16x16x32_bf16 v[84:87], v[150:153], v[174:177], v[84:87]
	v_mfma_f32_16x16x32_bf16 v[84:87], v[154:157], v[178:181], v[84:87]
	v_mfma_f32_16x16x32_bf16 v[100:103], v[150:153], v[166:169], v[100:103]
	v_mfma_f32_16x16x32_bf16 v[100:103], v[154:157], v[170:173], v[100:103]
	v_mfma_f32_16x16x32_bf16 v[116:119], v[150:153], v[158:161], v[116:119]
	v_mfma_f32_16x16x32_bf16 v[116:119], v[154:157], v[162:165], v[116:119]
	s_barrier
	s_add_i32 s42, 0, 0x14000
	s_add_i32 s39, s39, s24
	ds_read_b128 v[216:219], v139 offset:16384
	ds_read_b128 v[220:223], v139 offset:17408
	ds_read_b128 v[224:227], v139 offset:18432
	ds_read_b128 v[228:231], v139 offset:19456
	s_mov_b32 m0, s39
	s_add_u32 s98, s18, s58
	s_addc_u32 s99, s19, s59
	global_load_lds_dwordx4 v184, s[18:19]
	s_add_i32 m0, s39, 0x2000
	s_nop 0
	global_load_lds_dwordx4 v128, s[18:19]
	s_barrier
	s_waitcnt lgkmcnt(0)
	v_mfma_f32_16x16x32_bf16 v[120:123], v[216:219], v[158:161], v[120:123]
	v_mfma_f32_16x16x32_bf16 v[120:123], v[220:223], v[162:165], v[120:123]
	v_mfma_f32_16x16x32_bf16 v[104:107], v[216:219], v[166:169], v[104:107]
	v_mfma_f32_16x16x32_bf16 v[104:107], v[220:223], v[170:173], v[104:107]
	v_mfma_f32_16x16x32_bf16 v[88:91], v[216:219], v[174:177], v[88:91]
	v_mfma_f32_16x16x32_bf16 v[88:91], v[220:223], v[178:181], v[88:91]
	v_mfma_f32_16x16x32_bf16 v[72:75], v[216:219], v[208:211], v[72:75]
	v_mfma_f32_16x16x32_bf16 v[72:75], v[220:223], v[212:215], v[72:75]
	v_mfma_f32_16x16x32_bf16 v[64:67], v[224:227], v[208:211], v[64:67]
	v_mfma_f32_16x16x32_bf16 v[64:67], v[228:231], v[212:215], v[64:67]
	v_mfma_f32_16x16x32_bf16 v[80:83], v[224:227], v[174:177], v[80:83]
	v_mfma_f32_16x16x32_bf16 v[80:83], v[228:231], v[178:181], v[80:83]
	v_mfma_f32_16x16x32_bf16 v[96:99], v[224:227], v[166:169], v[96:99]
	v_mfma_f32_16x16x32_bf16 v[96:99], v[228:231], v[170:173], v[96:99]
	v_mfma_f32_16x16x32_bf16 v[112:115], v[224:227], v[158:161], v[112:115]
	v_mfma_f32_16x16x32_bf16 v[112:115], v[228:231], v[162:165], v[112:115]
	s_mov_b32 m0, s15
	s_barrier
	ds_read_b128 v[158:161], v141 offset:16384
	ds_read_b128 v[162:165], v141 offset:17408
	ds_read_b128 v[166:169], v141 offset:18432
	ds_read_b128 v[170:173], v141 offset:19456
	ds_read_b128 v[174:177], v141 offset:20480
	ds_read_b128 v[178:181], v141 offset:21504
	ds_read_b128 v[208:211], v141 offset:22528
	ds_read_b128 v[212:215], v141 offset:23552
	global_load_lds_dwordx4 v132, s[20:21]
	s_add_u32 s100, s20, s58
	s_addc_u32 s101, s21, s59
	s_mov_b32 m0, s26
	s_nop 0
	global_load_lds_dwordx4 v130, s[20:21]
	s_barrier
	s_waitcnt lgkmcnt(0)
	v_mfma_f32_16x16x32_bf16 v[60:63], v[142:145], v[158:161], v[60:63]
	v_mfma_f32_16x16x32_bf16 v[60:63], v[146:149], v[162:165], v[60:63]
	v_mfma_f32_16x16x32_bf16 v[44:47], v[142:145], v[166:169], v[44:47]
	v_mfma_f32_16x16x32_bf16 v[44:47], v[146:149], v[170:173], v[44:47]
	v_mfma_f32_16x16x32_bf16 v[28:31], v[142:145], v[174:177], v[28:31]
	v_mfma_f32_16x16x32_bf16 v[28:31], v[146:149], v[178:181], v[28:31]
	v_mfma_f32_16x16x32_bf16 v[12:15], v[142:145], v[208:211], v[12:15]
	v_mfma_f32_16x16x32_bf16 v[12:15], v[146:149], v[212:215], v[12:15]
	v_mfma_f32_16x16x32_bf16 v[4:7], v[150:153], v[208:211], v[4:7]
	v_mfma_f32_16x16x32_bf16 v[4:7], v[154:157], v[212:215], v[4:7]
	v_mfma_f32_16x16x32_bf16 v[20:23], v[150:153], v[174:177], v[20:23]
	v_mfma_f32_16x16x32_bf16 v[20:23], v[154:157], v[178:181], v[20:23]
	v_mfma_f32_16x16x32_bf16 v[36:39], v[150:153], v[166:169], v[36:39]
	v_mfma_f32_16x16x32_bf16 v[36:39], v[154:157], v[170:173], v[36:39]
	v_mfma_f32_16x16x32_bf16 v[52:55], v[150:153], v[158:161], v[52:55]
	v_mfma_f32_16x16x32_bf16 v[52:55], v[154:157], v[162:165], v[52:55]
	s_barrier
	s_add_u32 s40, s18, 0x80000
	s_addc_u32 s41, s19, 0
	s_add_i32 s39, s42, s24
	s_mov_b32 m0, s39
	s_nop 0
	global_load_lds_dwordx4 v184, s[40:41]
	s_add_i32 m0, s39, 0x2000
	s_nop 0
	global_load_lds_dwordx4 v128, s[40:41]
	s_waitcnt vmcnt(6)
	s_barrier
; #define PG8_STAGE(bufoff, gbase, voff) do { _Pragma("unroll") for (int _i = 0; _i < 2; ++_i) \
;         __builtin_amdgcn_global_load_lds((const unsigned*)((const char*)(gbase) + (voff)[_i]), (LAS unsigned*)(lds + (bufoff) + ldsw + _i * 8192), 16, 0, 0); } while (0)
; #define PG8_LDA(dst, b, h) do { _Pragma("unroll") for (int m = 0; m < 4; ++m) _Pragma("unroll") for (int k = 0; k < 2; ++k) dst[m][k] = *(const LAS bf16x8*)(lds + PG8_SA(b, h) + aoff + m * 2048 + k * 1024); } while (0)
; #define PG8_LDB(dst, b, h) do { _Pragma("unroll") for (int n = 0; n < 2; ++n) _Pragma("unroll") for (int k = 0; k < 2; ++k) dst[n][k] = *(const LAS bf16x8*)(lds + PG8_SB(b, h) + boff + n * 2048 + k * 1024); } while (0)
; #define PG8_MMA(ai, bj, At, Bt) do { __builtin_amdgcn_s_setprio(1); _Pragma("unroll") for (int m = 0; m < 4; ++m) _Pragma("unroll") for (int n = 0; n < 2; ++n) _Pragma("unroll") for (int k = 0; k < 2; ++k) \
;         acc[ai][bj][m][n] = __builtin_amdgcn_mfma_f32_16x16x32_bf16(Bt[n][k], At[m][k], acc[ai][bj][m][n], 0, 0, 0); __builtin_amdgcn_s_setprio(0); } while (0)
; #define PG8_WAIT_V(n) asm volatile("s_waitcnt vmcnt(" #n ")" ::: "memory")
; #define PG8_WAIT_L(n) asm volatile("s_waitcnt lgkmcnt(" #n ")" ::: "memory")
; #define PG8_BAR __builtin_amdgcn_s_barrier()
; #define PG8_SCHED __builtin_amdgcn_sched_barrier(0)
; template <class Epi>
; __device__ __forceinline__ void gemm_phase(LAS unsigned char* lds, const Gemm g, const StaticOrder& S, const Epi& E) {
;     ...
;             PG8_WAIT_V(6); PG8_BAR; PG8_MMA(1, 1, At, B1); PG8_BAR;
;             PG8_LDB(B0, 1, 0); PG8_SCHED; PG8_LDA(At, 1, 0); PG8_STAGE(PG8_SA(0, 1), a2 + hstep, voffA);
;             PG8_WAIT_L(8); PG8_BAR; PG8_WAIT_L(0); PG8_MMA(0, 0, At, B0); PG8_BAR; PG8_SCHED;
;             PG8_LDB(B1, 1, 1); PG8_STAGE(PG8_SB(1, 0), b3, voffB);
;             PG8_BAR; PG8_WAIT_L(0); PG8_MMA(0, 1, At, B1); PG8_BAR;
;             PG8_LDA(At, 1, 1); PG8_STAGE(PG8_SA(1, 0), a3, voffA);
;             PG8_BAR; PG8_WAIT_L(0); PG8_MMA(1, 0, At, B0); PG8_BAR; PG8_SCHED;
	v_mfma_f32_16x16x32_bf16 v[56:59], v[216:219], v[158:161], v[56:59]
	v_mfma_f32_16x16x32_bf16 v[56:59], v[220:223], v[162:165], v[56:59]
	v_mfma_f32_16x16x32_bf16 v[40:43], v[216:219], v[166:169], v[40:43]
	v_mfma_f32_16x16x32_bf16 v[40:43], v[220:223], v[170:173], v[40:43]
	v_mfma_f32_16x16x32_bf16 v[24:27], v[216:219], v[174:177], v[24:27]
	v_mfma_f32_16x16x32_bf16 v[24:27], v[220:223], v[178:181], v[24:27]
	v_mfma_f32_16x16x32_bf16 v[8:11], v[216:219], v[208:211], v[8:11]
	v_mfma_f32_16x16x32_bf16 v[8:11], v[220:223], v[212:215], v[8:11]
	v_mfma_f32_16x16x32_bf16 v[0:3], v[224:227], v[208:211], v[0:3]
	v_mfma_f32_16x16x32_bf16 v[0:3], v[228:231], v[212:215], v[0:3]
	v_mfma_f32_16x16x32_bf16 v[16:19], v[224:227], v[174:177], v[16:19]
	v_mfma_f32_16x16x32_bf16 v[16:19], v[228:231], v[178:181], v[16:19]
	v_mfma_f32_16x16x32_bf16 v[32:35], v[224:227], v[166:169], v[32:35]
	v_mfma_f32_16x16x32_bf16 v[32:35], v[228:231], v[170:173], v[32:35]
	v_mfma_f32_16x16x32_bf16 v[48:51], v[224:227], v[158:161], v[48:51]
	v_mfma_f32_16x16x32_bf16 v[48:51], v[228:231], v[162:165], v[48:51]
	s_add_i32 s39, 0, 0x18000
	s_barrier
	ds_read_b128 v[142:145], v139 offset:32768
	ds_read_b128 v[146:149], v139 offset:33792
	ds_read_b128 v[150:153], v139 offset:34816
	ds_read_b128 v[154:157], v139 offset:35840
	s_add_u32 s20, s20, 0x80000
	s_addc_u32 s21, s21, 0
	s_mov_b32 m0, s27
	ds_read_b128 v[158:161], v141 offset:32768
	ds_read_b128 v[162:165], v141 offset:33792
	ds_read_b128 v[166:169], v141 offset:34816
	ds_read_b128 v[170:173], v141 offset:35840
	ds_read_b128 v[174:177], v141 offset:36864
	ds_read_b128 v[178:181], v141 offset:37888
	ds_read_b128 v[208:211], v141 offset:38912
	ds_read_b128 v[212:215], v141 offset:39936
	global_load_lds_dwordx4 v132, s[20:21]
	s_mov_b32 m0, s28
	s_nop 0
	global_load_lds_dwordx4 v130, s[20:21]
	s_waitcnt lgkmcnt(8)
	s_barrier
	s_waitcnt lgkmcnt(0)
	v_mfma_f32_16x16x32_bf16 v[124:127], v[142:145], v[158:161], v[124:127]
	v_mfma_f32_16x16x32_bf16 v[124:127], v[146:149], v[162:165], v[124:127]
	v_mfma_f32_16x16x32_bf16 v[108:111], v[142:145], v[166:169], v[108:111]
	v_mfma_f32_16x16x32_bf16 v[108:111], v[146:149], v[170:173], v[108:111]
	v_mfma_f32_16x16x32_bf16 v[92:95], v[142:145], v[174:177], v[92:95]
	v_mfma_f32_16x16x32_bf16 v[92:95], v[146:149], v[178:181], v[92:95]
	v_mfma_f32_16x16x32_bf16 v[76:79], v[142:145], v[208:211], v[76:79]
	v_mfma_f32_16x16x32_bf16 v[76:79], v[146:149], v[212:215], v[76:79]
	v_mfma_f32_16x16x32_bf16 v[68:71], v[150:153], v[208:211], v[68:71]
	v_mfma_f32_16x16x32_bf16 v[68:71], v[154:157], v[212:215], v[68:71]
	v_mfma_f32_16x16x32_bf16 v[84:87], v[150:153], v[174:177], v[84:87]
	v_mfma_f32_16x16x32_bf16 v[84:87], v[154:157], v[178:181], v[84:87]
	v_mfma_f32_16x16x32_bf16 v[100:103], v[150:153], v[166:169], v[100:103]
	v_mfma_f32_16x16x32_bf16 v[100:103], v[154:157], v[170:173], v[100:103]
	v_mfma_f32_16x16x32_bf16 v[116:119], v[150:153], v[158:161], v[116:119]
	v_mfma_f32_16x16x32_bf16 v[116:119], v[154:157], v[162:165], v[116:119]
	s_barrier
	s_add_i32 s20, 0, 0x1c000
	s_add_i32 s21, s39, s24
	s_mov_b32 m0, s21
	ds_read_b128 v[216:219], v139 offset:49152
	ds_read_b128 v[220:223], v139 offset:50176
	ds_read_b128 v[224:227], v139 offset:51200
	ds_read_b128 v[228:231], v139 offset:52224
	global_load_lds_dwordx4 v184, s[98:99]
	s_add_i32 m0, s21, 0x2000
	s_nop 0
	global_load_lds_dwordx4 v128, s[98:99]
	s_barrier
	s_waitcnt lgkmcnt(0)
	v_mfma_f32_16x16x32_bf16 v[120:123], v[216:219], v[158:161], v[120:123]
	v_mfma_f32_16x16x32_bf16 v[120:123], v[220:223], v[162:165], v[120:123]
	v_mfma_f32_16x16x32_bf16 v[104:107], v[216:219], v[166:169], v[104:107]
	v_mfma_f32_16x16x32_bf16 v[104:107], v[220:223], v[170:173], v[104:107]
	v_mfma_f32_16x16x32_bf16 v[88:91], v[216:219], v[174:177], v[88:91]
	v_mfma_f32_16x16x32_bf16 v[88:91], v[220:223], v[178:181], v[88:91]
	v_mfma_f32_16x16x32_bf16 v[72:75], v[216:219], v[208:211], v[72:75]
	v_mfma_f32_16x16x32_bf16 v[72:75], v[220:223], v[212:215], v[72:75]
	v_mfma_f32_16x16x32_bf16 v[64:67], v[224:227], v[208:211], v[64:67]
	v_mfma_f32_16x16x32_bf16 v[64:67], v[228:231], v[212:215], v[64:67]
	v_mfma_f32_16x16x32_bf16 v[80:83], v[224:227], v[174:177], v[80:83]
	v_mfma_f32_16x16x32_bf16 v[80:83], v[228:231], v[178:181], v[80:83]
	v_mfma_f32_16x16x32_bf16 v[96:99], v[224:227], v[166:169], v[96:99]
	v_mfma_f32_16x16x32_bf16 v[96:99], v[228:231], v[170:173], v[96:99]
	v_mfma_f32_16x16x32_bf16 v[112:115], v[224:227], v[158:161], v[112:115]
	v_mfma_f32_16x16x32_bf16 v[112:115], v[228:231], v[162:165], v[112:115]
	s_mov_b32 m0, s29
	s_barrier
	ds_read_b128 v[158:161], v141 offset:49152
	ds_read_b128 v[162:165], v141 offset:50176
	ds_read_b128 v[166:169], v141 offset:51200
	ds_read_b128 v[170:173], v141 offset:52224
	ds_read_b128 v[174:177], v141 offset:53248
	ds_read_b128 v[178:181], v141 offset:54272
	ds_read_b128 v[208:211], v141 offset:55296
	ds_read_b128 v[212:215], v141 offset:56320
	global_load_lds_dwordx4 v132, s[100:101]
	s_mov_b32 m0, s30
	s_nop 0
	global_load_lds_dwordx4 v130, s[100:101]
	s_barrier
	s_waitcnt lgkmcnt(0)
	v_mfma_f32_16x16x32_bf16 v[60:63], v[142:145], v[158:161], v[60:63]
	v_mfma_f32_16x16x32_bf16 v[60:63], v[146:149], v[162:165], v[60:63]
	v_mfma_f32_16x16x32_bf16 v[44:47], v[142:145], v[166:169], v[44:47]
	v_mfma_f32_16x16x32_bf16 v[44:47], v[146:149], v[170:173], v[44:47]
	v_mfma_f32_16x16x32_bf16 v[28:31], v[142:145], v[174:177], v[28:31]
	v_mfma_f32_16x16x32_bf16 v[28:31], v[146:149], v[178:181], v[28:31]
	v_mfma_f32_16x16x32_bf16 v[12:15], v[142:145], v[208:211], v[12:15]
	v_mfma_f32_16x16x32_bf16 v[12:15], v[146:149], v[212:215], v[12:15]
	v_mfma_f32_16x16x32_bf16 v[4:7], v[150:153], v[208:211], v[4:7]
	v_mfma_f32_16x16x32_bf16 v[4:7], v[154:157], v[212:215], v[4:7]
	v_mfma_f32_16x16x32_bf16 v[20:23], v[150:153], v[174:177], v[20:23]
	v_mfma_f32_16x16x32_bf16 v[20:23], v[154:157], v[178:181], v[20:23]
	v_mfma_f32_16x16x32_bf16 v[36:39], v[150:153], v[166:169], v[36:39]
	v_mfma_f32_16x16x32_bf16 v[36:39], v[154:157], v[170:173], v[36:39]
	v_mfma_f32_16x16x32_bf16 v[52:55], v[150:153], v[158:161], v[52:55]
	v_mfma_f32_16x16x32_bf16 v[52:55], v[154:157], v[162:165], v[52:55]
	s_barrier
; __device__ __forceinline__ unsigned pk2(float lo, float hi) { unsigned r; asm("v_cvt_pk_bf16_f32 %0, %1, %2" : "=v"(r) : "v"(lo), "v"(hi)); return r; }
; __device__ __forceinline__ float sigmoidf_(float x) { return __builtin_amdgcn_rcpf(1.0f + __builtin_amdgcn_exp2f(-1.4426950408889634f * x)); }
; #define PG8_STAGE(bufoff, gbase, voff) do { _Pragma("unroll") for (int _i = 0; _i < 2; ++_i) \
;         __builtin_amdgcn_global_load_lds((const unsigned*)((const char*)(gbase) + (voff)[_i]), (LAS unsigned*)(lds + (bufoff) + ldsw + _i * 8192), 16, 0, 0); } while (0)
; #define PG8_MMA(ai, bj, At, Bt) do { __builtin_amdgcn_s_setprio(1); _Pragma("unroll") for (int m = 0; m < 4; ++m) _Pragma("unroll") for (int n = 0; n < 2; ++n) _Pragma("unroll") for (int k = 0; k < 2; ++k) \
;         acc[ai][bj][m][n] = __builtin_amdgcn_mfma_f32_16x16x32_bf16(Bt[n][k], At[m][k], acc[ai][bj][m][n], 0, 0, 0); __builtin_amdgcn_s_setprio(0); } while (0)
; #define PG8_WAIT_V(n) asm volatile("s_waitcnt vmcnt(" #n ")" ::: "memory")
; #define PG8_BAR __builtin_amdgcn_s_barrier()
; template <class Epi>
; __device__ __forceinline__ void gemm_phase(LAS unsigned char* lds, const Gemm g, const StaticOrder& S, const Epi& E) {
;     ...
;             PG8_STAGE(PG8_SB(1, 1), b3 + hstep, voffB);
;             PG8_WAIT_V(6); PG8_BAR; PG8_MMA(1, 1, At, B1); PG8_BAR;
;     __device__ __forceinline__ void operator()(const Acc& acc, const Unit& u, int wr, int wc, int fr, int fq) const {
;         const int row0 = u.pm * 256 + wr * 64 + fr, col0 = u.pn * 128 + wc * 32 + 8 * fq;
; #pragma unroll
;         for (int ai = 0; ai < 2; ++ai)
; #pragma unroll
;             for (int m = 0; m < 4; ++m) {
;                 float h[8];
; #pragma unroll
;                 for (int n = 0; n < 2; ++n)
; #pragma unroll
;                     for (int j = 0; j < 4; ++j) { const float gv = acc[ai][0][m][n][j], uv = acc[ai][1][m][n][j]; h[n * 4 + j] = gv * sigmoidf_(gv) * uv; }
;                 u32x4 w; w.x = pk2(h[0], h[1]); w.y = pk2(h[2], h[3]); w.z = pk2(h[4], h[5]); w.w = pk2(h[6], h[7]);
;                 *(u32x4*)(H + (size_t)(row0 + ai * 128 + m * 16) * DFF + col0) = w;
	s_add_u32 s18, s18, 0x80080
	s_addc_u32 s19, s19, 0
	s_add_i32 s20, s20, s24
	s_mov_b32 m0, s20
	s_nop 0
	global_load_lds_dwordx4 v184, s[18:19]
	s_add_i32 m0, s20, 0x2000
	s_nop 0
	global_load_lds_dwordx4 v128, s[18:19]
	s_waitcnt vmcnt(6)
	s_barrier
	v_mfma_f32_16x16x32_bf16 v[56:59], v[216:219], v[158:161], v[56:59]
	v_mfma_f32_16x16x32_bf16 v[56:59], v[220:223], v[162:165], v[56:59]
	v_mfma_f32_16x16x32_bf16 v[40:43], v[216:219], v[166:169], v[40:43]
	v_mfma_f32_16x16x32_bf16 v[40:43], v[220:223], v[170:173], v[40:43]
	v_mfma_f32_16x16x32_bf16 v[24:27], v[216:219], v[174:177], v[24:27]
	v_mfma_f32_16x16x32_bf16 v[24:27], v[220:223], v[178:181], v[24:27]
	v_mfma_f32_16x16x32_bf16 v[8:11], v[216:219], v[208:211], v[8:11]
	v_mfma_f32_16x16x32_bf16 v[8:11], v[220:223], v[212:215], v[8:11]
	v_mfma_f32_16x16x32_bf16 v[0:3], v[224:227], v[208:211], v[0:3]
	v_mfma_f32_16x16x32_bf16 v[0:3], v[228:231], v[212:215], v[0:3]
	v_mfma_f32_16x16x32_bf16 v[16:19], v[224:227], v[174:177], v[16:19]
	v_mfma_f32_16x16x32_bf16 v[16:19], v[228:231], v[178:181], v[16:19]
	v_mfma_f32_16x16x32_bf16 v[32:35], v[224:227], v[166:169], v[32:35]
	v_mfma_f32_16x16x32_bf16 v[32:35], v[228:231], v[170:173], v[32:35]
	v_mfma_f32_16x16x32_bf16 v[48:51], v[224:227], v[158:161], v[48:51]
	v_mfma_f32_16x16x32_bf16 v[48:51], v[228:231], v[162:165], v[48:51]
	s_add_i32 s38, s38, 2
	s_add_u32 s16, s16, 0x100
	s_addc_u32 s17, s17, 0
	s_add_u32 s36, s36, 0x100
	s_addc_u32 s37, s37, 0
	s_cmp_gt_u32 s38, 29
	s_barrier
	s_cbranch_scc0 .LBB0_721
	v_mul_f32_e32 v143, 0xbfb8aa3b, v124
	v_exp_f32_e32 v143, v143
	v_lshl_or_b32 v144, s3, 7, v140
	v_lshl_add_u32 v142, s14, 8, v138
	v_ashrrev_i32_e32 v145, 31, v144
	v_add_f32_e32 v143, 1.0, v143
	v_rcp_f32_e32 v143, v143
	s_movk_i32 s1, 0x2c00
	s_and_b64 vcc, exec, s[6:7]
	s_mov_b32 s3, s0
	v_mul_f32_e32 v124, v124, v143
	v_mul_f32_e32 v120, v124, v120
	v_mul_f32_e32 v124, 0xbfb8aa3b, v125
	v_exp_f32_e32 v124, v124
	s_mov_b32 s14, s8
	s_mov_b64 s[18:19], s[12:13]
	v_add_f32_e32 v124, 1.0, v124
	v_rcp_f32_e32 v124, v124
	s_nop 0
	v_mul_f32_e32 v124, v125, v124
	v_mul_f32_e32 v121, v124, v121
	v_mul_f32_e32 v124, 0xbfb8aa3b, v126
	v_exp_f32_e32 v124, v124
	s_nop 0
	v_add_f32_e32 v124, 1.0, v124
	v_rcp_f32_e32 v124, v124
	s_nop 0
	v_mul_f32_e32 v124, v126, v124
	v_mul_f32_e32 v122, v124, v122
	v_mul_f32_e32 v124, 0xbfb8aa3b, v127
	v_exp_f32_e32 v124, v124
	s_nop 0
	v_add_f32_e32 v124, 1.0, v124
	v_rcp_f32_e32 v124, v124
	s_nop 0
	v_mul_f32_e32 v124, v127, v124
	v_mul_f32_e32 v123, v124, v123
	v_mul_f32_e32 v124, 0xbfb8aa3b, v116
	v_exp_f32_e32 v124, v124
	s_nop 0
	v_add_f32_e32 v124, 1.0, v124
	v_rcp_f32_e32 v124, v124
	s_nop 0
	v_mul_f32_e32 v116, v116, v124
	v_mul_f32_e32 v112, v116, v112
	v_mul_f32_e32 v116, 0xbfb8aa3b, v117
	v_exp_f32_e32 v116, v116
	s_nop 0
	v_add_f32_e32 v116, 1.0, v116
	v_rcp_f32_e32 v116, v116
	s_nop 0
	v_mul_f32_e32 v116, v117, v116
	v_mul_f32_e32 v113, v116, v113
	v_mul_f32_e32 v116, 0xbfb8aa3b, v118
	v_exp_f32_e32 v116, v116
	v_cvt_pk_bf16_f32 v117, v122, v123
	s_nop 0
	v_add_f32_e32 v116, 1.0, v116
	v_rcp_f32_e32 v116, v116
	s_nop 0
	v_mul_f32_e32 v116, v118, v116
	v_mul_f32_e32 v114, v116, v114
	v_mul_f32_e32 v116, 0xbfb8aa3b, v119
	v_exp_f32_e32 v116, v116
	v_cvt_pk_bf16_f32 v118, v112, v113
	v_mov_b64_e32 v[112:113], s[66:67]
	v_add_f32_e32 v116, 1.0, v116
	v_rcp_f32_e32 v116, v116
	s_nop 0
	v_mul_f32_e32 v116, v119, v116
	v_mul_f32_e32 v115, v116, v115
	v_cvt_pk_bf16_f32 v116, v120, v121
	v_cvt_pk_bf16_f32 v119, v114, v115
	v_mad_i64_i32 v[120:121], s[16:17], v142, s1, v[112:113]
	v_lshlrev_b64 v[114:115], 1, v[144:145]
	v_lshl_add_u64 v[120:121], v[120:121], 0, v[114:115]
	global_store_dwordx4 v[120:121], v[116:119], off
	s_nop 1
	v_mul_f32_e32 v116, 0xbfb8aa3b, v108
	v_exp_f32_e32 v116, v116
	s_nop 0
	v_add_f32_e32 v116, 1.0, v116
	v_rcp_f32_e32 v116, v116
	s_nop 0
	v_mul_f32_e32 v108, v108, v116
	v_mul_f32_e32 v104, v108, v104
	v_mul_f32_e32 v108, 0xbfb8aa3b, v109
	v_exp_f32_e32 v108, v108
	s_nop 0
	v_add_f32_e32 v108, 1.0, v108
	v_rcp_f32_e32 v108, v108
	s_nop 0
	v_mul_f32_e32 v108, v109, v108
	v_mul_f32_e32 v105, v108, v105
	v_mul_f32_e32 v108, 0xbfb8aa3b, v110
	v_exp_f32_e32 v108, v108
	s_nop 0
	v_add_f32_e32 v108, 1.0, v108
	v_rcp_f32_e32 v108, v108
	s_nop 0
	v_mul_f32_e32 v108, v110, v108
	v_mul_f32_e32 v106, v108, v106
	v_mul_f32_e32 v108, 0xbfb8aa3b, v111
	v_exp_f32_e32 v108, v108
	s_nop 0
	v_add_f32_e32 v108, 1.0, v108
	v_rcp_f32_e32 v108, v108
	s_nop 0
	v_mul_f32_e32 v108, v111, v108
	v_mul_f32_e32 v107, v108, v107
	v_mul_f32_e32 v108, 0xbfb8aa3b, v100
	v_exp_f32_e32 v108, v108
	s_nop 0
	v_add_f32_e32 v108, 1.0, v108
	v_rcp_f32_e32 v108, v108
	s_nop 0
	v_mul_f32_e32 v100, v100, v108
	v_mul_f32_e32 v100, v100, v96
	v_mul_f32_e32 v96, 0xbfb8aa3b, v101
	v_exp_f32_e32 v96, v96
	s_nop 0
	v_add_f32_e32 v96, 1.0, v96
	v_rcp_f32_e32 v96, v96
	s_nop 0
	v_mul_f32_e32 v96, v101, v96
	v_mul_f32_e32 v101, v96, v97
	v_mul_f32_e32 v96, 0xbfb8aa3b, v102
	v_exp_f32_e32 v96, v96
	v_cvt_pk_bf16_f32 v97, v106, v107
	s_nop 0
	v_add_f32_e32 v96, 1.0, v96
	v_rcp_f32_e32 v96, v96
	s_nop 0
	v_mul_f32_e32 v96, v102, v96
	v_mul_f32_e32 v102, v96, v98
	v_mul_f32_e32 v96, 0xbfb8aa3b, v103
	v_exp_f32_e32 v96, v96
	v_cvt_pk_bf16_f32 v98, v100, v101
	v_or_b32_e32 v100, 16, v142
	v_mad_i64_i32 v[100:101], s[16:17], v100, s1, v[112:113]
	v_add_f32_e32 v96, 1.0, v96
	v_rcp_f32_e32 v96, v96
	v_lshl_add_u64 v[100:101], v[100:101], 0, v[114:115]
	v_mul_f32_e32 v96, v103, v96
	v_mul_f32_e32 v99, v96, v99
	v_cvt_pk_bf16_f32 v96, v104, v105
	v_cvt_pk_bf16_f32 v99, v102, v99
	global_store_dwordx4 v[100:101], v[96:99], off
	s_nop 1
; __device__ __forceinline__ unsigned pk2(float lo, float hi) { unsigned r; asm("v_cvt_pk_bf16_f32 %0, %1, %2" : "=v"(r) : "v"(lo), "v"(hi)); return r; }
; __device__ __forceinline__ float sigmoidf_(float x) { return __builtin_amdgcn_rcpf(1.0f + __builtin_amdgcn_exp2f(-1.4426950408889634f * x)); }
;     __device__ __forceinline__ void operator()(const Acc& acc, const Unit& u, int wr, int wc, int fr, int fq) const {
;     ...
;             for (int m = 0; m < 4; ++m) {
;                 float h[8];
; #pragma unroll
;                 for (int n = 0; n < 2; ++n)
; #pragma unroll
;                     for (int j = 0; j < 4; ++j) { const float gv = acc[ai][0][m][n][j], uv = acc[ai][1][m][n][j]; h[n * 4 + j] = gv * sigmoidf_(gv) * uv; }
;                 u32x4 w; w.x = pk2(h[0], h[1]); w.y = pk2(h[2], h[3]); w.z = pk2(h[4], h[5]); w.w = pk2(h[6], h[7]);
;                 *(u32x4*)(H + (size_t)(row0 + ai * 128 + m * 16) * DFF + col0) = w;
	v_mul_f32_e32 v96, 0xbfb8aa3b, v92
	v_exp_f32_e32 v96, v96
	s_nop 0
	v_add_f32_e32 v96, 1.0, v96
	v_rcp_f32_e32 v96, v96
	s_nop 0
	v_mul_f32_e32 v92, v92, v96
	v_mul_f32_e32 v88, v92, v88
	v_mul_f32_e32 v92, 0xbfb8aa3b, v93
	v_exp_f32_e32 v92, v92
	s_nop 0
	v_add_f32_e32 v92, 1.0, v92
	v_rcp_f32_e32 v92, v92
	s_nop 0
	v_mul_f32_e32 v92, v93, v92
	v_mul_f32_e32 v89, v92, v89
	v_mul_f32_e32 v92, 0xbfb8aa3b, v94
	v_exp_f32_e32 v92, v92
	s_nop 0
	v_add_f32_e32 v92, 1.0, v92
	v_rcp_f32_e32 v92, v92
	s_nop 0
	v_mul_f32_e32 v92, v94, v92
	v_mul_f32_e32 v90, v92, v90
	v_mul_f32_e32 v92, 0xbfb8aa3b, v95
	v_exp_f32_e32 v92, v92
	s_nop 0
	v_add_f32_e32 v92, 1.0, v92
	v_rcp_f32_e32 v92, v92
	s_nop 0
	v_mul_f32_e32 v92, v95, v92
	v_mul_f32_e32 v91, v92, v91
	v_mul_f32_e32 v92, 0xbfb8aa3b, v84
	v_exp_f32_e32 v92, v92
	s_nop 0
	v_add_f32_e32 v92, 1.0, v92
	v_rcp_f32_e32 v92, v92
	s_nop 0
	v_mul_f32_e32 v84, v84, v92
	v_mul_f32_e32 v84, v84, v80
	v_mul_f32_e32 v80, 0xbfb8aa3b, v85
	v_exp_f32_e32 v80, v80
	s_nop 0
	v_add_f32_e32 v80, 1.0, v80
	v_rcp_f32_e32 v80, v80
	s_nop 0
	v_mul_f32_e32 v80, v85, v80
	v_mul_f32_e32 v85, v80, v81
	v_mul_f32_e32 v80, 0xbfb8aa3b, v86
	v_exp_f32_e32 v80, v80
	v_cvt_pk_bf16_f32 v81, v90, v91
	s_nop 0
	v_add_f32_e32 v80, 1.0, v80
	v_rcp_f32_e32 v80, v80
	s_nop 0
	v_mul_f32_e32 v80, v86, v80
	v_mul_f32_e32 v86, v80, v82
	v_mul_f32_e32 v80, 0xbfb8aa3b, v87
	v_exp_f32_e32 v80, v80
	v_cvt_pk_bf16_f32 v82, v84, v85
	v_or_b32_e32 v84, 32, v142
	v_mad_i64_i32 v[84:85], s[16:17], v84, s1, v[112:113]
	v_add_f32_e32 v80, 1.0, v80
	v_rcp_f32_e32 v80, v80
	v_lshl_add_u64 v[84:85], v[84:85], 0, v[114:115]
	v_mul_f32_e32 v80, v87, v80
	v_mul_f32_e32 v83, v80, v83
	v_cvt_pk_bf16_f32 v80, v88, v89
	v_cvt_pk_bf16_f32 v83, v86, v83
	global_store_dwordx4 v[84:85], v[80:83], off
	s_nop 1
	v_mul_f32_e32 v80, 0xbfb8aa3b, v76
	v_exp_f32_e32 v80, v80
	s_nop 0
	v_add_f32_e32 v80, 1.0, v80
	v_rcp_f32_e32 v80, v80
	s_nop 0
	v_mul_f32_e32 v76, v76, v80
	v_mul_f32_e32 v72, v76, v72
	v_mul_f32_e32 v76, 0xbfb8aa3b, v77
	v_exp_f32_e32 v76, v76
	s_nop 0
	v_add_f32_e32 v76, 1.0, v76
	v_rcp_f32_e32 v76, v76
	s_nop 0
	v_mul_f32_e32 v76, v77, v76
	v_mul_f32_e32 v73, v76, v73
	v_mul_f32_e32 v76, 0xbfb8aa3b, v78
	v_exp_f32_e32 v76, v76
	s_nop 0
	v_add_f32_e32 v76, 1.0, v76
	v_rcp_f32_e32 v76, v76
	s_nop 0
	v_mul_f32_e32 v76, v78, v76
	v_mul_f32_e32 v74, v76, v74
	v_mul_f32_e32 v76, 0xbfb8aa3b, v79
	v_exp_f32_e32 v76, v76
	s_nop 0
	v_add_f32_e32 v76, 1.0, v76
	v_rcp_f32_e32 v76, v76
	s_nop 0
	v_mul_f32_e32 v76, v79, v76
	v_mul_f32_e32 v75, v76, v75
	v_mul_f32_e32 v76, 0xbfb8aa3b, v68
	v_exp_f32_e32 v76, v76
	s_nop 0
	v_add_f32_e32 v76, 1.0, v76
	v_rcp_f32_e32 v76, v76
	s_nop 0
	v_mul_f32_e32 v68, v68, v76
	v_mul_f32_e32 v68, v68, v64
	v_mul_f32_e32 v64, 0xbfb8aa3b, v69
	v_exp_f32_e32 v64, v64
	s_nop 0
	v_add_f32_e32 v64, 1.0, v64
	v_rcp_f32_e32 v64, v64
	s_nop 0
	v_mul_f32_e32 v64, v69, v64
	v_mul_f32_e32 v69, v64, v65
	v_mul_f32_e32 v64, 0xbfb8aa3b, v70
	v_exp_f32_e32 v64, v64
	v_cvt_pk_bf16_f32 v65, v74, v75
	s_nop 0
	v_add_f32_e32 v64, 1.0, v64
	v_rcp_f32_e32 v64, v64
	s_nop 0
	v_mul_f32_e32 v64, v70, v64
	v_mul_f32_e32 v70, v64, v66
	v_mul_f32_e32 v64, 0xbfb8aa3b, v71
	v_exp_f32_e32 v64, v64
	v_cvt_pk_bf16_f32 v66, v68, v69
	v_or_b32_e32 v68, 48, v142
	v_mad_i64_i32 v[68:69], s[16:17], v68, s1, v[112:113]
	v_add_f32_e32 v64, 1.0, v64
	v_rcp_f32_e32 v64, v64
	v_lshl_add_u64 v[68:69], v[68:69], 0, v[114:115]
	v_mul_f32_e32 v64, v71, v64
	v_mul_f32_e32 v67, v64, v67
	v_cvt_pk_bf16_f32 v64, v72, v73
	v_cvt_pk_bf16_f32 v67, v70, v67
	global_store_dwordx4 v[68:69], v[64:67], off
	s_nop 1
	v_mul_f32_e32 v65, 0xbfb8aa3b, v60
	v_exp_f32_e32 v65, v65
	v_add_u32_e32 v64, 0x80, v142
	v_add_f32_e32 v65, 1.0, v65
	v_rcp_f32_e32 v65, v65
	s_nop 0
	v_mul_f32_e32 v60, v60, v65
	v_mul_f32_e32 v56, v60, v56
	v_mul_f32_e32 v60, 0xbfb8aa3b, v61
	v_exp_f32_e32 v60, v60
	s_nop 0
	v_add_f32_e32 v60, 1.0, v60
	v_rcp_f32_e32 v60, v60
	s_nop 0
	v_mul_f32_e32 v60, v61, v60
	v_mul_f32_e32 v57, v60, v57
	v_mul_f32_e32 v60, 0xbfb8aa3b, v62
	v_exp_f32_e32 v60, v60
	s_nop 0
	v_add_f32_e32 v60, 1.0, v60
	v_rcp_f32_e32 v60, v60
	s_nop 0
	v_mul_f32_e32 v60, v62, v60
	v_mul_f32_e32 v58, v60, v58
	v_mul_f32_e32 v60, 0xbfb8aa3b, v63
	v_exp_f32_e32 v60, v60
	s_nop 0
	v_add_f32_e32 v60, 1.0, v60
	v_rcp_f32_e32 v60, v60
	s_nop 0
	v_mul_f32_e32 v60, v63, v60
	v_mul_f32_e32 v59, v60, v59
	v_mul_f32_e32 v60, 0xbfb8aa3b, v52
	v_exp_f32_e32 v60, v60
	s_nop 0
	v_add_f32_e32 v60, 1.0, v60
	v_rcp_f32_e32 v60, v60
	s_nop 0
	v_mul_f32_e32 v52, v52, v60
	v_mul_f32_e32 v52, v52, v48
	v_mul_f32_e32 v48, 0xbfb8aa3b, v53
	v_exp_f32_e32 v48, v48
	s_nop 0
	v_add_f32_e32 v48, 1.0, v48
	v_rcp_f32_e32 v48, v48
	s_nop 0
	v_mul_f32_e32 v48, v53, v48
	v_mul_f32_e32 v53, v48, v49
	v_mul_f32_e32 v48, 0xbfb8aa3b, v54
	v_exp_f32_e32 v48, v48
	v_cvt_pk_bf16_f32 v49, v58, v59
	s_nop 0
	v_add_f32_e32 v48, 1.0, v48
	v_rcp_f32_e32 v48, v48
	s_nop 0
	v_mul_f32_e32 v48, v54, v48
	v_mul_f32_e32 v54, v48, v50
	v_mul_f32_e32 v48, 0xbfb8aa3b, v55
	v_exp_f32_e32 v48, v48
	v_cvt_pk_bf16_f32 v50, v52, v53
	v_mad_i64_i32 v[52:53], s[16:17], v64, s1, v[112:113]
	v_add_f32_e32 v48, 1.0, v48
	v_rcp_f32_e32 v48, v48
	v_lshl_add_u64 v[52:53], v[52:53], 0, v[114:115]
	v_mul_f32_e32 v48, v55, v48
	v_mul_f32_e32 v51, v48, v51
	v_cvt_pk_bf16_f32 v48, v56, v57
	v_cvt_pk_bf16_f32 v51, v54, v51
	global_store_dwordx4 v[52:53], v[48:51], off
	s_nop 1
	v_mul_f32_e32 v48, 0xbfb8aa3b, v44
; __device__ __forceinline__ unsigned pk2(float lo, float hi) { unsigned r; asm("v_cvt_pk_bf16_f32 %0, %1, %2" : "=v"(r) : "v"(lo), "v"(hi)); return r; }
; __device__ __forceinline__ float sigmoidf_(float x) { return __builtin_amdgcn_rcpf(1.0f + __builtin_amdgcn_exp2f(-1.4426950408889634f * x)); }
; #define PG8_WAIT_V(n) asm volatile("s_waitcnt vmcnt(" #n ")" ::: "memory")
; #define PG8_BAR __builtin_amdgcn_s_barrier()
; template <class Epi>
; __device__ __forceinline__ void gemm_phase(LAS unsigned char* lds, const Gemm g, const StaticOrder& S, const Epi& E) {
;     ...
;         cur = nxt; cA = nA; cB = nB; ++ui;
;     }
;     PG8_WAIT_V(0);
;     if (wr == 0) PG8_BAR;
;     PG8_BAR;
;     __device__ __forceinline__ void operator()(const Acc& acc, const Unit& u, int wr, int wc, int fr, int fq) const {
;     ...
;             for (int m = 0; m < 4; ++m) {
;                 float h[8];
; #pragma unroll
;                 for (int n = 0; n < 2; ++n)
; #pragma unroll
;                     for (int j = 0; j < 4; ++j) { const float gv = acc[ai][0][m][n][j], uv = acc[ai][1][m][n][j]; h[n * 4 + j] = gv * sigmoidf_(gv) * uv; }
;                 u32x4 w; w.x = pk2(h[0], h[1]); w.y = pk2(h[2], h[3]); w.z = pk2(h[4], h[5]); w.w = pk2(h[6], h[7]);
;                 *(u32x4*)(H + (size_t)(row0 + ai * 128 + m * 16) * DFF + col0) = w;
	v_exp_f32_e32 v48, v48
	s_nop 0
	v_add_f32_e32 v48, 1.0, v48
	v_rcp_f32_e32 v48, v48
	s_nop 0
	v_mul_f32_e32 v44, v44, v48
	v_mul_f32_e32 v40, v44, v40
	v_mul_f32_e32 v44, 0xbfb8aa3b, v45
	v_exp_f32_e32 v44, v44
	s_nop 0
	v_add_f32_e32 v44, 1.0, v44
	v_rcp_f32_e32 v44, v44
	s_nop 0
	v_mul_f32_e32 v44, v45, v44
	v_mul_f32_e32 v41, v44, v41
	v_mul_f32_e32 v44, 0xbfb8aa3b, v46
	v_exp_f32_e32 v44, v44
	s_nop 0
	v_add_f32_e32 v44, 1.0, v44
	v_rcp_f32_e32 v44, v44
	s_nop 0
	v_mul_f32_e32 v44, v46, v44
	v_mul_f32_e32 v42, v44, v42
	v_mul_f32_e32 v44, 0xbfb8aa3b, v47
	v_exp_f32_e32 v44, v44
	s_nop 0
	v_add_f32_e32 v44, 1.0, v44
	v_rcp_f32_e32 v44, v44
	s_nop 0
	v_mul_f32_e32 v44, v47, v44
	v_mul_f32_e32 v43, v44, v43
	v_mul_f32_e32 v44, 0xbfb8aa3b, v36
	v_exp_f32_e32 v44, v44
	s_nop 0
	v_add_f32_e32 v44, 1.0, v44
	v_rcp_f32_e32 v44, v44
	s_nop 0
	v_mul_f32_e32 v36, v36, v44
	v_mul_f32_e32 v36, v36, v32
	v_mul_f32_e32 v32, 0xbfb8aa3b, v37
	v_exp_f32_e32 v32, v32
	s_nop 0
	v_add_f32_e32 v32, 1.0, v32
	v_rcp_f32_e32 v32, v32
	s_nop 0
	v_mul_f32_e32 v32, v37, v32
	v_mul_f32_e32 v37, v32, v33
	v_mul_f32_e32 v32, 0xbfb8aa3b, v38
	v_exp_f32_e32 v32, v32
	v_cvt_pk_bf16_f32 v33, v42, v43
	s_nop 0
	v_add_f32_e32 v32, 1.0, v32
	v_rcp_f32_e32 v32, v32
	s_nop 0
	v_mul_f32_e32 v32, v38, v32
	v_mul_f32_e32 v38, v32, v34
	v_mul_f32_e32 v32, 0xbfb8aa3b, v39
	v_exp_f32_e32 v32, v32
	v_cvt_pk_bf16_f32 v34, v36, v37
	v_add_u32_e32 v36, 0x90, v142
	v_mad_i64_i32 v[36:37], s[16:17], v36, s1, v[112:113]
	v_add_f32_e32 v32, 1.0, v32
	v_rcp_f32_e32 v32, v32
	v_lshl_add_u64 v[36:37], v[36:37], 0, v[114:115]
	v_mul_f32_e32 v32, v39, v32
	v_mul_f32_e32 v35, v32, v35
	v_cvt_pk_bf16_f32 v32, v40, v41
	v_cvt_pk_bf16_f32 v35, v38, v35
	global_store_dwordx4 v[36:37], v[32:35], off
	s_nop 1
	v_mul_f32_e32 v32, 0xbfb8aa3b, v28
	v_exp_f32_e32 v32, v32
	s_nop 0
	v_add_f32_e32 v32, 1.0, v32
	v_rcp_f32_e32 v32, v32
	s_nop 0
	v_mul_f32_e32 v28, v28, v32
	v_mul_f32_e32 v24, v28, v24
	v_mul_f32_e32 v28, 0xbfb8aa3b, v29
	v_exp_f32_e32 v28, v28
	s_nop 0
	v_add_f32_e32 v28, 1.0, v28
	v_rcp_f32_e32 v28, v28
	s_nop 0
	v_mul_f32_e32 v28, v29, v28
	v_mul_f32_e32 v25, v28, v25
	v_mul_f32_e32 v28, 0xbfb8aa3b, v30
	v_exp_f32_e32 v28, v28
	s_nop 0
	v_add_f32_e32 v28, 1.0, v28
	v_rcp_f32_e32 v28, v28
	s_nop 0
	v_mul_f32_e32 v28, v30, v28
	v_mul_f32_e32 v26, v28, v26
	v_mul_f32_e32 v28, 0xbfb8aa3b, v31
	v_exp_f32_e32 v28, v28
	s_nop 0
	v_add_f32_e32 v28, 1.0, v28
	v_rcp_f32_e32 v28, v28
	s_nop 0
	v_mul_f32_e32 v28, v31, v28
	v_mul_f32_e32 v27, v28, v27
	v_mul_f32_e32 v28, 0xbfb8aa3b, v20
	v_exp_f32_e32 v28, v28
	s_nop 0
	v_add_f32_e32 v28, 1.0, v28
	v_rcp_f32_e32 v28, v28
	s_nop 0
	v_mul_f32_e32 v20, v20, v28
	v_mul_f32_e32 v20, v20, v16
	v_mul_f32_e32 v16, 0xbfb8aa3b, v21
	v_exp_f32_e32 v16, v16
	s_nop 0
	v_add_f32_e32 v16, 1.0, v16
	v_rcp_f32_e32 v16, v16
	s_nop 0
	v_mul_f32_e32 v16, v21, v16
	v_mul_f32_e32 v21, v16, v17
	v_mul_f32_e32 v16, 0xbfb8aa3b, v22
	v_exp_f32_e32 v16, v16
	v_cvt_pk_bf16_f32 v17, v26, v27
	s_nop 0
	v_add_f32_e32 v16, 1.0, v16
	v_rcp_f32_e32 v16, v16
	s_nop 0
	v_mul_f32_e32 v16, v22, v16
	v_mul_f32_e32 v22, v16, v18
	v_mul_f32_e32 v16, 0xbfb8aa3b, v23
	v_exp_f32_e32 v16, v16
	v_cvt_pk_bf16_f32 v18, v20, v21
	v_add_u32_e32 v20, 0xa0, v142
	v_mad_i64_i32 v[20:21], s[16:17], v20, s1, v[112:113]
	v_add_f32_e32 v16, 1.0, v16
	v_rcp_f32_e32 v16, v16
	v_lshl_add_u64 v[20:21], v[20:21], 0, v[114:115]
	v_mul_f32_e32 v16, v23, v16
	v_mul_f32_e32 v19, v16, v19
	v_cvt_pk_bf16_f32 v16, v24, v25
	v_cvt_pk_bf16_f32 v19, v22, v19
	global_store_dwordx4 v[20:21], v[16:19], off
	s_nop 1
	v_mul_f32_e32 v16, 0xbfb8aa3b, v12
	v_exp_f32_e32 v16, v16
	s_nop 0
	v_add_f32_e32 v16, 1.0, v16
	v_rcp_f32_e32 v16, v16
	s_nop 0
	v_mul_f32_e32 v12, v12, v16
	v_mul_f32_e32 v8, v12, v8
	v_mul_f32_e32 v12, 0xbfb8aa3b, v13
	v_exp_f32_e32 v12, v12
	s_nop 0
	v_add_f32_e32 v12, 1.0, v12
	v_rcp_f32_e32 v12, v12
	s_nop 0
	v_mul_f32_e32 v12, v13, v12
	v_mul_f32_e32 v9, v12, v9
	v_mul_f32_e32 v12, 0xbfb8aa3b, v14
	v_exp_f32_e32 v12, v12
	s_nop 0
	v_add_f32_e32 v12, 1.0, v12
	v_rcp_f32_e32 v12, v12
	s_nop 0
	v_mul_f32_e32 v12, v14, v12
	v_mul_f32_e32 v10, v12, v10
	v_mul_f32_e32 v12, 0xbfb8aa3b, v15
	v_exp_f32_e32 v12, v12
	s_nop 0
	v_add_f32_e32 v12, 1.0, v12
	v_rcp_f32_e32 v12, v12
	s_nop 0
	v_mul_f32_e32 v12, v15, v12
	v_mul_f32_e32 v11, v12, v11
	v_mul_f32_e32 v12, 0xbfb8aa3b, v4
	v_exp_f32_e32 v12, v12
	s_nop 0
	v_add_f32_e32 v12, 1.0, v12
	v_rcp_f32_e32 v12, v12
	s_nop 0
	v_mul_f32_e32 v4, v4, v12
	v_mul_f32_e32 v4, v4, v0
	v_mul_f32_e32 v0, 0xbfb8aa3b, v5
	v_exp_f32_e32 v0, v0
	s_nop 0
	v_add_f32_e32 v0, 1.0, v0
	v_rcp_f32_e32 v0, v0
	s_nop 0
	v_mul_f32_e32 v0, v5, v0
	v_mul_f32_e32 v5, v0, v1
	v_mul_f32_e32 v0, 0xbfb8aa3b, v6
	v_exp_f32_e32 v0, v0
	v_cvt_pk_bf16_f32 v1, v10, v11
	s_nop 0
	v_add_f32_e32 v0, 1.0, v0
	v_rcp_f32_e32 v0, v0
	s_nop 0
	v_mul_f32_e32 v0, v6, v0
	v_mul_f32_e32 v6, v0, v2
	v_mul_f32_e32 v0, 0xbfb8aa3b, v7
	v_exp_f32_e32 v0, v0
	v_cvt_pk_bf16_f32 v2, v4, v5
	v_add_u32_e32 v4, 0xb0, v142
	v_mad_i64_i32 v[4:5], s[16:17], v4, s1, v[112:113]
	v_add_f32_e32 v0, 1.0, v0
	v_rcp_f32_e32 v0, v0
	v_lshl_add_u64 v[4:5], v[4:5], 0, v[114:115]
	s_mov_b64 s[16:17], s[10:11]
	v_mul_f32_e32 v0, v7, v0
	v_mul_f32_e32 v3, v0, v3
	v_cvt_pk_bf16_f32 v0, v8, v9
	v_cvt_pk_bf16_f32 v3, v6, v3
	global_store_dwordx4 v[4:5], v[0:3], off
	s_cbranch_vccz .LBB0_718
	s_waitcnt vmcnt(0)
	s_cmpk_gt_u32 s23, 0xff
	s_cbranch_scc1 .LBB0_725
	s_barrier
